# v46 + scalar loop-edge hoist: K-loop pointer/counter updates moved from the loop edge into the fourth load segment (8 loops)
# baseline (speedup 1.0000x reference)
.Lpeel_mid_0:
	s_add_i32 s33, 0, 0x18000
	s_add_i32 s55, 0, 0x1c000
	ds_read_b128 v[142:145], v151 offset:32768
	ds_read_b128 v[146:149], v151 offset:33792
	ds_read_b128 v[154:157], v151 offset:34816
	ds_read_b128 v[158:161], v151 offset:35840
	ds_read_b128 v[162:165], v151 offset:49152
	ds_read_b128 v[166:169], v151 offset:50176
	ds_read_b128 v[170:173], v151 offset:51200
	ds_read_b128 v[174:177], v151 offset:52224
	s_add_u32 s0, s28, 0x80000
	s_addc_u32 s1, s29, 0
	s_mov_b32 m0, s36
	ds_read_b128 v[178:181], v153 offset:32768
	ds_read_b128 v[182:185], v153 offset:33792
	ds_read_b128 v[186:189], v153 offset:34816
	ds_read_b128 v[190:193], v153 offset:35840
	ds_read_b128 v[194:197], v153 offset:36864
	ds_read_b128 v[198:201], v153 offset:37888
	ds_read_b128 v[208:211], v153 offset:38912
	ds_read_b128 v[212:215], v153 offset:39936
	global_load_lds_dwordx4 v130, s[0:1]
	s_mov_b32 m0, s37
	s_nop 0
	global_load_lds_dwordx4 v134, s[0:1]
	s_waitcnt vmcnt(8)
	s_waitcnt lgkmcnt(0)
	s_setprio 1
	s_barrier
	v_mfma_f32_16x16x32_bf16 v[126:129], v[142:145], v[178:181], v[126:129]
	v_mfma_f32_16x16x32_bf16 v[122:125], v[154:157], v[178:181], v[122:125]
	v_mfma_f32_16x16x32_bf16 v[110:113], v[142:145], v[186:189], v[110:113]
	v_mfma_f32_16x16x32_bf16 v[106:109], v[154:157], v[186:189], v[106:109]
	v_mfma_f32_16x16x32_bf16 v[94:97], v[142:145], v[194:197], v[94:97]
	v_mfma_f32_16x16x32_bf16 v[90:93], v[154:157], v[194:197], v[90:93]
	v_mfma_f32_16x16x32_bf16 v[78:81], v[142:145], v[208:211], v[78:81]
	v_mfma_f32_16x16x32_bf16 v[74:77], v[154:157], v[208:211], v[74:77]
	v_mfma_f32_16x16x32_bf16 v[126:129], v[146:149], v[182:185], v[126:129]
	v_mfma_f32_16x16x32_bf16 v[122:125], v[158:161], v[182:185], v[122:125]
	v_mfma_f32_16x16x32_bf16 v[110:113], v[146:149], v[190:193], v[110:113]
	v_mfma_f32_16x16x32_bf16 v[106:109], v[158:161], v[190:193], v[106:109]
	v_mfma_f32_16x16x32_bf16 v[94:97], v[146:149], v[198:201], v[94:97]
	v_mfma_f32_16x16x32_bf16 v[90:93], v[158:161], v[198:201], v[90:93]
	v_mfma_f32_16x16x32_bf16 v[78:81], v[146:149], v[212:215], v[78:81]
	v_mfma_f32_16x16x32_bf16 v[74:77], v[158:161], v[212:215], v[74:77]
	v_mfma_f32_16x16x32_bf16 v[118:121], v[162:165], v[178:181], v[118:121]
	v_mfma_f32_16x16x32_bf16 v[114:117], v[170:173], v[178:181], v[114:117]
	v_mfma_f32_16x16x32_bf16 v[102:105], v[162:165], v[186:189], v[102:105]
	v_mfma_f32_16x16x32_bf16 v[98:101], v[170:173], v[186:189], v[98:101]
	v_mfma_f32_16x16x32_bf16 v[86:89], v[162:165], v[194:197], v[86:89]
	v_mfma_f32_16x16x32_bf16 v[82:85], v[170:173], v[194:197], v[82:85]
	v_mfma_f32_16x16x32_bf16 v[70:73], v[162:165], v[208:211], v[70:73]
	v_mfma_f32_16x16x32_bf16 v[66:69], v[170:173], v[208:211], v[66:69]
	v_mfma_f32_16x16x32_bf16 v[118:121], v[166:169], v[182:185], v[118:121]
	v_mfma_f32_16x16x32_bf16 v[114:117], v[174:177], v[182:185], v[114:117]
	v_mfma_f32_16x16x32_bf16 v[102:105], v[166:169], v[190:193], v[102:105]
	v_mfma_f32_16x16x32_bf16 v[98:101], v[174:177], v[190:193], v[98:101]
	v_mfma_f32_16x16x32_bf16 v[86:89], v[166:169], v[198:201], v[86:89]
	v_mfma_f32_16x16x32_bf16 v[82:85], v[174:177], v[198:201], v[82:85]
	v_mfma_f32_16x16x32_bf16 v[70:73], v[166:169], v[212:215], v[70:73]
	v_mfma_f32_16x16x32_bf16 v[66:69], v[174:177], v[212:215], v[66:69]
	s_barrier
	s_setprio 0
	s_add_i32 s0, s33, s34
	s_add_u32 s100, s26, 0x80
	s_addc_u32 s101, s27, 0
	s_mov_b32 m0, s0
	ds_read_b128 v[178:181], v153 offset:49152
	ds_read_b128 v[182:185], v153 offset:50176
	ds_read_b128 v[186:189], v153 offset:51200
	ds_read_b128 v[190:193], v153 offset:52224
	ds_read_b128 v[194:197], v153 offset:53248
	ds_read_b128 v[198:201], v153 offset:54272
	ds_read_b128 v[208:211], v153 offset:55296
	ds_read_b128 v[212:215], v153 offset:56320
	global_load_lds_dwordx4 v132, s[100:101]
	s_add_i32 m0, s0, 0x2000
	s_add_u32 s100, s26, 0x80
	s_addc_u32 s101, s27, 0
	s_add_u32 s0, s26, 0x80080
	s_addc_u32 s1, s27, 0
	s_add_i32 s26, s55, s34
	global_load_lds_dwordx4 v136, s[100:101]
	s_mov_b32 m0, s26
	s_nop 0
	global_load_lds_dwordx4 v132, s[0:1]
	s_add_i32 m0, s26, 0x2000
	s_nop 0
	global_load_lds_dwordx4 v136, s[0:1]
	s_add_u32 s100, s28, 0x80
	s_addc_u32 s101, s29, 0
	s_mov_b32 m0, s39
	s_nop 0
	global_load_lds_dwordx4 v130, s[100:101]
	s_add_u32 s100, s28, 0x80
	s_addc_u32 s101, s29, 0
	s_mov_b32 m0, s40
	s_nop 0
	global_load_lds_dwordx4 v134, s[100:101]
	s_add_i32 s60, s60, 2
	s_add_u32 s24, s24, 0x100
	s_addc_u32 s25, s25, 0
	s_add_u32 s58, s58, 0x100
	s_addc_u32 s59, s59, 0
	s_waitcnt vmcnt(8)
	s_waitcnt lgkmcnt(0)
	s_setprio 1
	s_barrier
	v_mfma_f32_16x16x32_bf16 v[62:65], v[142:145], v[178:181], v[62:65]
	v_mfma_f32_16x16x32_bf16 v[58:61], v[154:157], v[178:181], v[58:61]
	v_mfma_f32_16x16x32_bf16 v[46:49], v[142:145], v[186:189], v[46:49]
	v_mfma_f32_16x16x32_bf16 v[42:45], v[154:157], v[186:189], v[42:45]
	v_mfma_f32_16x16x32_bf16 v[30:33], v[142:145], v[194:197], v[30:33]
	v_mfma_f32_16x16x32_bf16 v[26:29], v[154:157], v[194:197], v[26:29]
	v_mfma_f32_16x16x32_bf16 v[14:17], v[142:145], v[208:211], v[14:17]
	v_mfma_f32_16x16x32_bf16 v[10:13], v[154:157], v[208:211], v[10:13]
	v_mfma_f32_16x16x32_bf16 v[62:65], v[146:149], v[182:185], v[62:65]
	v_mfma_f32_16x16x32_bf16 v[58:61], v[158:161], v[182:185], v[58:61]
	v_mfma_f32_16x16x32_bf16 v[46:49], v[146:149], v[190:193], v[46:49]
	v_mfma_f32_16x16x32_bf16 v[42:45], v[158:161], v[190:193], v[42:45]
	v_mfma_f32_16x16x32_bf16 v[30:33], v[146:149], v[198:201], v[30:33]
	v_mfma_f32_16x16x32_bf16 v[26:29], v[158:161], v[198:201], v[26:29]
	v_mfma_f32_16x16x32_bf16 v[14:17], v[146:149], v[212:215], v[14:17]
	v_mfma_f32_16x16x32_bf16 v[10:13], v[158:161], v[212:215], v[10:13]
	v_mfma_f32_16x16x32_bf16 v[54:57], v[162:165], v[178:181], v[54:57]
	v_mfma_f32_16x16x32_bf16 v[50:53], v[170:173], v[178:181], v[50:53]
	v_mfma_f32_16x16x32_bf16 v[38:41], v[162:165], v[186:189], v[38:41]
	v_mfma_f32_16x16x32_bf16 v[34:37], v[170:173], v[186:189], v[34:37]
	v_mfma_f32_16x16x32_bf16 v[22:25], v[162:165], v[194:197], v[22:25]
	v_mfma_f32_16x16x32_bf16 v[18:21], v[170:173], v[194:197], v[18:21]
	v_mfma_f32_16x16x32_bf16 v[6:9], v[162:165], v[208:211], v[6:9]
	v_mfma_f32_16x16x32_bf16 v[2:5], v[170:173], v[208:211], v[2:5]
	v_mfma_f32_16x16x32_bf16 v[54:57], v[166:169], v[182:185], v[54:57]
	v_mfma_f32_16x16x32_bf16 v[50:53], v[174:177], v[182:185], v[50:53]
	v_mfma_f32_16x16x32_bf16 v[38:41], v[166:169], v[190:193], v[38:41]
	v_mfma_f32_16x16x32_bf16 v[34:37], v[174:177], v[190:193], v[34:37]
	v_mfma_f32_16x16x32_bf16 v[22:25], v[166:169], v[198:201], v[22:25]
	v_mfma_f32_16x16x32_bf16 v[18:21], v[174:177], v[198:201], v[18:21]
	v_mfma_f32_16x16x32_bf16 v[6:9], v[166:169], v[212:215], v[6:9]
	v_mfma_f32_16x16x32_bf16 v[2:5], v[174:177], v[212:215], v[2:5]
	s_barrier
	s_setprio 0
	s_cmp_gt_u32 s60, 29
	s_cbranch_scc0 .LBB0_394
	s_mov_b32 s101, 0x80000001
	s_and_b64 vcc, exec, s[14:15]
	s_cbranch_vccz .LBB0_397
	s_barrier

.LBB0_692:
	s_add_u32 s0, s18, 0xfff00080
	s_addc_u32 s1, s19, -1
	s_add_i32 s33, 0, 0x10000
	s_cmp_eq_u32 s61, 60
	s_cselect_b32 s23, s11, s1
	s_cselect_b32 s22, s49, s0
	s_cselect_b32 s21, s9, s60
	s_cselect_b32 s20, s58, s59
	s_add_i32 s55, 0, 0x14000
	ds_read_b128 v[78:81], v205
	ds_read_b128 v[86:89], v205 offset:1024
	ds_read_b128 v[94:97], v205 offset:2048
	ds_read_b128 v[98:101], v205 offset:3072
	ds_read_b128 v[106:109], v205 offset:16384
	ds_read_b128 v[110:113], v205 offset:17408
	ds_read_b128 v[126:129], v205 offset:18432
	ds_read_b128 v[134:137], v205 offset:19456
	s_add_i32 m0, s27, 0xc000
	ds_read_b128 v[146:149], v239
	ds_read_b128 v[158:161], v239 offset:1024
	ds_read_b128 v[166:169], v239 offset:2048
	ds_read_b128 v[174:177], v239 offset:3072
	ds_read_b128 v[178:181], v239 offset:4096
	ds_read_b128 v[182:185], v239 offset:5120
	ds_read_b128 v[186:189], v239 offset:6144
	ds_read_b128 v[190:193], v239 offset:7168
	global_load_lds_dwordx4 v214, s[18:19]
	s_add_i32 m0, s27, 0xe000
	s_nop 0
	global_load_lds_dwordx4 v216, s[18:19]
	s_waitcnt vmcnt(8)
	s_waitcnt lgkmcnt(0)
	s_setprio 1
	s_barrier
	v_mfma_f32_16x16x32_bf16 v[170:173], v[78:81], v[146:149], v[170:173]
	v_mfma_f32_16x16x32_bf16 v[162:165], v[94:97], v[146:149], v[162:165]
	v_mfma_f32_16x16x32_bf16 v[142:145], v[78:81], v[166:169], v[142:145]
	v_mfma_f32_16x16x32_bf16 v[138:141], v[94:97], v[166:169], v[138:141]
	v_mfma_f32_16x16x32_bf16 v[118:121], v[78:81], v[178:181], v[118:121]
	v_mfma_f32_16x16x32_bf16 v[114:117], v[94:97], v[178:181], v[114:117]
	v_mfma_f32_16x16x32_bf16 v[82:85], v[78:81], v[186:189], v[82:85]
	v_mfma_f32_16x16x32_bf16 v[74:77], v[94:97], v[186:189], v[74:77]
	v_mfma_f32_16x16x32_bf16 v[170:173], v[86:89], v[158:161], v[170:173]
	v_mfma_f32_16x16x32_bf16 v[162:165], v[98:101], v[158:161], v[162:165]
	v_mfma_f32_16x16x32_bf16 v[142:145], v[86:89], v[174:177], v[142:145]
	v_mfma_f32_16x16x32_bf16 v[138:141], v[98:101], v[174:177], v[138:141]
	v_mfma_f32_16x16x32_bf16 v[118:121], v[86:89], v[182:185], v[118:121]
	v_mfma_f32_16x16x32_bf16 v[114:117], v[98:101], v[182:185], v[114:117]
	v_mfma_f32_16x16x32_bf16 v[82:85], v[86:89], v[190:193], v[82:85]
	v_mfma_f32_16x16x32_bf16 v[74:77], v[98:101], v[190:193], v[74:77]
	v_mfma_f32_16x16x32_bf16 v[154:157], v[106:109], v[146:149], v[154:157]
	v_mfma_f32_16x16x32_bf16 v[130:133], v[106:109], v[166:169], v[130:133]
	v_mfma_f32_16x16x32_bf16 v[122:125], v[126:129], v[166:169], v[122:125]
	v_mfma_f32_16x16x32_bf16 v[102:105], v[106:109], v[178:181], v[102:105]
	v_mfma_f32_16x16x32_bf16 v[90:93], v[126:129], v[178:181], v[90:93]
	v_mfma_f32_16x16x32_bf16 v[70:73], v[106:109], v[186:189], v[70:73]
	v_mfma_f32_16x16x32_bf16 v[66:69], v[126:129], v[186:189], v[66:69]
	v_mfma_f32_16x16x32_bf16 v[154:157], v[110:113], v[158:161], v[154:157]
	v_mfma_f32_16x16x32_bf16 v[146:149], v[126:129], v[146:149], v[150:153]
	v_mfma_f32_16x16x32_bf16 v[130:133], v[110:113], v[174:177], v[130:133]
	v_mfma_f32_16x16x32_bf16 v[122:125], v[134:137], v[174:177], v[122:125]
	v_mfma_f32_16x16x32_bf16 v[102:105], v[110:113], v[182:185], v[102:105]
	v_mfma_f32_16x16x32_bf16 v[90:93], v[134:137], v[182:185], v[90:93]
	v_mfma_f32_16x16x32_bf16 v[70:73], v[110:113], v[190:193], v[70:73]
	v_mfma_f32_16x16x32_bf16 v[66:69], v[134:137], v[190:193], v[66:69]
	v_mfma_f32_16x16x32_bf16 v[146:149], v[134:137], v[158:161], v[146:149]
	s_barrier
	s_setprio 0
	s_add_i32 s0, s33, s26
	s_mov_b32 m0, s0
	ds_read_b128 v[150:153], v239 offset:16384
	ds_read_b128 v[158:161], v239 offset:17408
	ds_read_b128 v[166:169], v239 offset:18432
	ds_read_b128 v[174:177], v239 offset:19456
	ds_read_b128 v[178:181], v239 offset:20480
	ds_read_b128 v[182:185], v239 offset:21504
	ds_read_b128 v[186:189], v239 offset:22528
	ds_read_b128 v[190:193], v239 offset:23552
	global_load_lds_dwordx4 v202, s[20:21]
	s_add_i32 m0, s0, 0x2000
	s_add_u32 s0, s20, 0x100000
	s_addc_u32 s1, s21, 0
	s_add_i32 s33, s55, s26
	global_load_lds_dwordx4 v208, s[20:21]
	s_mov_b32 m0, s33
	s_nop 0
	global_load_lds_dwordx4 v202, s[0:1]
	s_add_i32 m0, s33, 0x2000
	s_nop 0
	global_load_lds_dwordx4 v208, s[0:1]
	s_mov_b32 m0, s27
	s_nop 0
	global_load_lds_dwordx4 v212, s[22:23]
	s_mov_b32 m0, s28
	s_nop 0
	global_load_lds_dwordx4 v210, s[22:23]
	s_waitcnt vmcnt(8)
	s_waitcnt lgkmcnt(0)
	s_setprio 1
	s_barrier
	v_mfma_f32_16x16x32_bf16 v[62:65], v[78:81], v[150:153], v[62:65]
	v_mfma_f32_16x16x32_bf16 v[58:61], v[94:97], v[150:153], v[58:61]
	v_mfma_f32_16x16x32_bf16 v[46:49], v[78:81], v[166:169], v[46:49]
	v_mfma_f32_16x16x32_bf16 v[42:45], v[94:97], v[166:169], v[42:45]
	v_mfma_f32_16x16x32_bf16 v[30:33], v[78:81], v[178:181], v[30:33]
	v_mfma_f32_16x16x32_bf16 v[26:29], v[94:97], v[178:181], v[26:29]
	v_mfma_f32_16x16x32_bf16 v[14:17], v[78:81], v[186:189], v[14:17]
	v_mfma_f32_16x16x32_bf16 v[10:13], v[94:97], v[186:189], v[10:13]
	v_mfma_f32_16x16x32_bf16 v[62:65], v[86:89], v[158:161], v[62:65]
	v_mfma_f32_16x16x32_bf16 v[58:61], v[98:101], v[158:161], v[58:61]
	v_mfma_f32_16x16x32_bf16 v[46:49], v[86:89], v[174:177], v[46:49]
	v_mfma_f32_16x16x32_bf16 v[42:45], v[98:101], v[174:177], v[42:45]
	v_mfma_f32_16x16x32_bf16 v[30:33], v[86:89], v[182:185], v[30:33]
	v_mfma_f32_16x16x32_bf16 v[26:29], v[98:101], v[182:185], v[26:29]
	v_mfma_f32_16x16x32_bf16 v[14:17], v[86:89], v[190:193], v[14:17]
	v_mfma_f32_16x16x32_bf16 v[10:13], v[98:101], v[190:193], v[10:13]
	v_mfma_f32_16x16x32_bf16 v[54:57], v[106:109], v[150:153], v[54:57]
	v_mfma_f32_16x16x32_bf16 v[50:53], v[126:129], v[150:153], v[50:53]
	v_mfma_f32_16x16x32_bf16 v[38:41], v[106:109], v[166:169], v[38:41]
	v_mfma_f32_16x16x32_bf16 v[34:37], v[126:129], v[166:169], v[34:37]
	v_mfma_f32_16x16x32_bf16 v[22:25], v[106:109], v[178:181], v[22:25]
	v_mfma_f32_16x16x32_bf16 v[18:21], v[126:129], v[178:181], v[18:21]
	v_mfma_f32_16x16x32_bf16 v[6:9], v[106:109], v[186:189], v[6:9]
	v_mfma_f32_16x16x32_bf16 v[2:5], v[126:129], v[186:189], v[2:5]
	v_mfma_f32_16x16x32_bf16 v[54:57], v[110:113], v[158:161], v[54:57]
	v_mfma_f32_16x16x32_bf16 v[50:53], v[134:137], v[158:161], v[50:53]
	v_mfma_f32_16x16x32_bf16 v[38:41], v[110:113], v[174:177], v[38:41]
	v_mfma_f32_16x16x32_bf16 v[34:37], v[134:137], v[174:177], v[34:37]
	v_mfma_f32_16x16x32_bf16 v[22:25], v[110:113], v[182:185], v[22:25]
	v_mfma_f32_16x16x32_bf16 v[18:21], v[134:137], v[182:185], v[18:21]
	v_mfma_f32_16x16x32_bf16 v[6:9], v[110:113], v[190:193], v[6:9]
	v_mfma_f32_16x16x32_bf16 v[2:5], v[134:137], v[190:193], v[2:5]
	s_barrier
	s_setprio 0
	s_add_i32 s33, 0, 0x18000
	s_add_i32 s55, 0, 0x1c000
	ds_read_b128 v[78:81], v205 offset:32768
	ds_read_b128 v[86:89], v205 offset:33792
	ds_read_b128 v[94:97], v205 offset:34816
	ds_read_b128 v[98:101], v205 offset:35840
	ds_read_b128 v[106:109], v205 offset:49152
	ds_read_b128 v[110:113], v205 offset:50176
	ds_read_b128 v[126:129], v205 offset:51200
	ds_read_b128 v[134:137], v205 offset:52224
	s_add_u32 s0, s22, 0x100000
	s_addc_u32 s1, s23, 0
	s_mov_b32 m0, s29
	ds_read_b128 v[150:153], v239 offset:32768
	ds_read_b128 v[158:161], v239 offset:33792
	ds_read_b128 v[166:169], v239 offset:34816
	ds_read_b128 v[174:177], v239 offset:35840
	ds_read_b128 v[178:181], v239 offset:36864
	ds_read_b128 v[182:185], v239 offset:37888
	ds_read_b128 v[186:189], v239 offset:38912
	ds_read_b128 v[190:193], v239 offset:39936
	global_load_lds_dwordx4 v212, s[0:1]
	s_mov_b32 m0, s30
	s_nop 0
	global_load_lds_dwordx4 v210, s[0:1]
	s_waitcnt vmcnt(8)
	s_waitcnt lgkmcnt(0)
	s_setprio 1
	s_barrier
	v_mfma_f32_16x16x32_bf16 v[170:173], v[78:81], v[150:153], v[170:173]
	v_mfma_f32_16x16x32_bf16 v[162:165], v[94:97], v[150:153], v[162:165]
	v_mfma_f32_16x16x32_bf16 v[142:145], v[78:81], v[166:169], v[142:145]
	v_mfma_f32_16x16x32_bf16 v[138:141], v[94:97], v[166:169], v[138:141]
	v_mfma_f32_16x16x32_bf16 v[118:121], v[78:81], v[178:181], v[118:121]
	v_mfma_f32_16x16x32_bf16 v[114:117], v[94:97], v[178:181], v[114:117]
	v_mfma_f32_16x16x32_bf16 v[82:85], v[78:81], v[186:189], v[82:85]
	v_mfma_f32_16x16x32_bf16 v[74:77], v[94:97], v[186:189], v[74:77]
	v_mfma_f32_16x16x32_bf16 v[170:173], v[86:89], v[158:161], v[170:173]
	v_mfma_f32_16x16x32_bf16 v[162:165], v[98:101], v[158:161], v[162:165]
	v_mfma_f32_16x16x32_bf16 v[142:145], v[86:89], v[174:177], v[142:145]
	v_mfma_f32_16x16x32_bf16 v[138:141], v[98:101], v[174:177], v[138:141]
	v_mfma_f32_16x16x32_bf16 v[118:121], v[86:89], v[182:185], v[118:121]
	v_mfma_f32_16x16x32_bf16 v[114:117], v[98:101], v[182:185], v[114:117]
	v_mfma_f32_16x16x32_bf16 v[82:85], v[86:89], v[190:193], v[82:85]
	v_mfma_f32_16x16x32_bf16 v[74:77], v[98:101], v[190:193], v[74:77]
	v_mfma_f32_16x16x32_bf16 v[154:157], v[106:109], v[150:153], v[154:157]
	v_mfma_f32_16x16x32_bf16 v[146:149], v[126:129], v[150:153], v[146:149]
	v_mfma_f32_16x16x32_bf16 v[130:133], v[106:109], v[166:169], v[130:133]
	v_mfma_f32_16x16x32_bf16 v[122:125], v[126:129], v[166:169], v[122:125]
	v_mfma_f32_16x16x32_bf16 v[102:105], v[106:109], v[178:181], v[102:105]
	v_mfma_f32_16x16x32_bf16 v[90:93], v[126:129], v[178:181], v[90:93]
	v_mfma_f32_16x16x32_bf16 v[70:73], v[106:109], v[186:189], v[70:73]
	v_mfma_f32_16x16x32_bf16 v[66:69], v[126:129], v[186:189], v[66:69]
	v_mfma_f32_16x16x32_bf16 v[154:157], v[110:113], v[158:161], v[154:157]
	v_mfma_f32_16x16x32_bf16 v[150:153], v[134:137], v[158:161], v[146:149]
	v_mfma_f32_16x16x32_bf16 v[130:133], v[110:113], v[174:177], v[130:133]
	v_mfma_f32_16x16x32_bf16 v[122:125], v[134:137], v[174:177], v[122:125]
	v_mfma_f32_16x16x32_bf16 v[102:105], v[110:113], v[182:185], v[102:105]
	v_mfma_f32_16x16x32_bf16 v[90:93], v[134:137], v[182:185], v[90:93]
	v_mfma_f32_16x16x32_bf16 v[70:73], v[110:113], v[190:193], v[70:73]
	v_mfma_f32_16x16x32_bf16 v[66:69], v[134:137], v[190:193], v[66:69]
	s_barrier
	s_setprio 0
	s_add_i32 s0, s33, s26
	s_add_u32 s100, s20, 0x80
	s_addc_u32 s101, s21, 0
	s_mov_b32 m0, s0
	ds_read_b128 v[146:149], v239 offset:49152
	ds_read_b128 v[158:161], v239 offset:50176
	ds_read_b128 v[166:169], v239 offset:51200
	ds_read_b128 v[174:177], v239 offset:52224
	ds_read_b128 v[178:181], v239 offset:53248
	ds_read_b128 v[182:185], v239 offset:54272
	ds_read_b128 v[186:189], v239 offset:55296
	ds_read_b128 v[190:193], v239 offset:56320
	global_load_lds_dwordx4 v202, s[100:101]
	s_add_i32 m0, s0, 0x2000
	s_add_u32 s100, s20, 0x80
	s_addc_u32 s101, s21, 0
	s_add_u32 s0, s20, 0x100080
	s_addc_u32 s1, s21, 0
	s_add_i32 s20, s55, s26
	global_load_lds_dwordx4 v208, s[100:101]
	s_mov_b32 m0, s20
	s_nop 0
	global_load_lds_dwordx4 v202, s[0:1]
	s_add_i32 m0, s20, 0x2000
	s_nop 0
	global_load_lds_dwordx4 v208, s[0:1]
	s_add_u32 s100, s22, 0x80
	s_addc_u32 s101, s23, 0
	s_mov_b32 m0, s35
	s_nop 0
	global_load_lds_dwordx4 v212, s[100:101]
	s_add_u32 s100, s22, 0x80
	s_addc_u32 s101, s23, 0
	s_mov_b32 m0, s36
	s_nop 0
	global_load_lds_dwordx4 v210, s[100:101]
	s_add_i32 s61, s61, 2
	s_add_u32 s18, s18, 0x100
	s_addc_u32 s19, s19, 0
	s_add_u32 s59, s59, 0x100
	s_addc_u32 s60, s60, 0
	s_waitcnt vmcnt(8)
	s_waitcnt lgkmcnt(0)
	s_setprio 1
	s_barrier
	v_mfma_f32_16x16x32_bf16 v[62:65], v[78:81], v[146:149], v[62:65]
	v_mfma_f32_16x16x32_bf16 v[58:61], v[94:97], v[146:149], v[58:61]
	v_mfma_f32_16x16x32_bf16 v[46:49], v[78:81], v[166:169], v[46:49]
	v_mfma_f32_16x16x32_bf16 v[42:45], v[94:97], v[166:169], v[42:45]
	v_mfma_f32_16x16x32_bf16 v[30:33], v[78:81], v[178:181], v[30:33]
	v_mfma_f32_16x16x32_bf16 v[26:29], v[94:97], v[178:181], v[26:29]
	v_mfma_f32_16x16x32_bf16 v[14:17], v[78:81], v[186:189], v[14:17]
	v_mfma_f32_16x16x32_bf16 v[10:13], v[94:97], v[186:189], v[10:13]
	v_mfma_f32_16x16x32_bf16 v[62:65], v[86:89], v[158:161], v[62:65]
	v_mfma_f32_16x16x32_bf16 v[58:61], v[98:101], v[158:161], v[58:61]
	v_mfma_f32_16x16x32_bf16 v[46:49], v[86:89], v[174:177], v[46:49]
	v_mfma_f32_16x16x32_bf16 v[42:45], v[98:101], v[174:177], v[42:45]
	v_mfma_f32_16x16x32_bf16 v[30:33], v[86:89], v[182:185], v[30:33]
	v_mfma_f32_16x16x32_bf16 v[26:29], v[98:101], v[182:185], v[26:29]
	v_mfma_f32_16x16x32_bf16 v[14:17], v[86:89], v[190:193], v[14:17]
	v_mfma_f32_16x16x32_bf16 v[10:13], v[98:101], v[190:193], v[10:13]
	v_mfma_f32_16x16x32_bf16 v[54:57], v[106:109], v[146:149], v[54:57]
	v_mfma_f32_16x16x32_bf16 v[50:53], v[126:129], v[146:149], v[50:53]
	v_mfma_f32_16x16x32_bf16 v[38:41], v[106:109], v[166:169], v[38:41]
	v_mfma_f32_16x16x32_bf16 v[34:37], v[126:129], v[166:169], v[34:37]
	v_mfma_f32_16x16x32_bf16 v[22:25], v[106:109], v[178:181], v[22:25]
	v_mfma_f32_16x16x32_bf16 v[18:21], v[126:129], v[178:181], v[18:21]
	v_mfma_f32_16x16x32_bf16 v[6:9], v[106:109], v[186:189], v[6:9]
	v_mfma_f32_16x16x32_bf16 v[2:5], v[126:129], v[186:189], v[2:5]
	v_mfma_f32_16x16x32_bf16 v[54:57], v[110:113], v[158:161], v[54:57]
	v_mfma_f32_16x16x32_bf16 v[50:53], v[134:137], v[158:161], v[50:53]
	v_mfma_f32_16x16x32_bf16 v[38:41], v[110:113], v[174:177], v[38:41]
	v_mfma_f32_16x16x32_bf16 v[34:37], v[134:137], v[174:177], v[34:37]
	v_mfma_f32_16x16x32_bf16 v[22:25], v[110:113], v[182:185], v[22:25]
	v_mfma_f32_16x16x32_bf16 v[18:21], v[134:137], v[182:185], v[18:21]
	v_mfma_f32_16x16x32_bf16 v[6:9], v[110:113], v[190:193], v[6:9]
	v_mfma_f32_16x16x32_bf16 v[2:5], v[134:137], v[190:193], v[2:5]
	s_barrier
	s_setprio 0
	s_cmp_gt_u32 s61, 61
	s_cbranch_scc0 .LBB0_692
	s_and_b64 vcc, exec, s[6:7]
	s_cbranch_vccz .LBB0_695
	s_barrier

.LBB0_712:
	s_add_u32 s0, s18, 0xfff00080
	s_addc_u32 s1, s19, -1
	s_add_i32 s33, 0, 0x10000
	s_cmp_eq_u32 s49, 4
	s_cselect_b32 s23, s15, s1
	s_cselect_b32 s22, s14, s0
	s_cselect_b32 s21, s17, s11
	s_cselect_b32 s20, s16, s9
	s_add_i32 s55, 0, 0x14000
	ds_read_b128 v[140:143], v136
	ds_read_b128 v[144:147], v136 offset:1024
	ds_read_b128 v[148:151], v136 offset:2048
	ds_read_b128 v[152:155], v136 offset:3072
	ds_read_b128 v[156:159], v136 offset:16384
	ds_read_b128 v[160:163], v136 offset:17408
	ds_read_b128 v[164:167], v136 offset:18432
	ds_read_b128 v[168:171], v136 offset:19456
	s_add_i32 m0, s27, 0xc000
	ds_read_b128 v[172:175], v139
	ds_read_b128 v[176:179], v139 offset:1024
	ds_read_b128 v[180:183], v139 offset:2048
	ds_read_b128 v[184:187], v139 offset:3072
	ds_read_b128 v[188:191], v139 offset:4096
	ds_read_b128 v[192:195], v139 offset:5120
	ds_read_b128 v[196:199], v139 offset:6144
	ds_read_b128 v[208:211], v139 offset:7168
	global_load_lds_dwordx4 v132, s[18:19]
	s_add_i32 m0, s27, 0xe000
	s_nop 0
	global_load_lds_dwordx4 v134, s[18:19]
	s_waitcnt vmcnt(8)
	s_waitcnt lgkmcnt(0)
	s_setprio 1
	s_barrier
	v_mfma_f32_16x16x32_bf16 v[126:129], v[140:143], v[172:175], v[126:129]
	v_mfma_f32_16x16x32_bf16 v[122:125], v[148:151], v[172:175], v[122:125]
	v_mfma_f32_16x16x32_bf16 v[118:121], v[140:143], v[180:183], v[118:121]
	v_mfma_f32_16x16x32_bf16 v[114:117], v[148:151], v[180:183], v[114:117]
	v_mfma_f32_16x16x32_bf16 v[106:109], v[140:143], v[188:191], v[106:109]
	v_mfma_f32_16x16x32_bf16 v[98:101], v[148:151], v[188:191], v[98:101]
	v_mfma_f32_16x16x32_bf16 v[90:93], v[140:143], v[196:199], v[90:93]
	v_mfma_f32_16x16x32_bf16 v[82:85], v[148:151], v[196:199], v[82:85]
	v_mfma_f32_16x16x32_bf16 v[126:129], v[144:147], v[176:179], v[126:129]
	v_mfma_f32_16x16x32_bf16 v[122:125], v[152:155], v[176:179], v[122:125]
	v_mfma_f32_16x16x32_bf16 v[118:121], v[144:147], v[184:187], v[118:121]
	v_mfma_f32_16x16x32_bf16 v[114:117], v[152:155], v[184:187], v[114:117]
	v_mfma_f32_16x16x32_bf16 v[106:109], v[144:147], v[192:195], v[106:109]
	v_mfma_f32_16x16x32_bf16 v[98:101], v[152:155], v[192:195], v[98:101]
	v_mfma_f32_16x16x32_bf16 v[90:93], v[144:147], v[208:211], v[90:93]
	v_mfma_f32_16x16x32_bf16 v[82:85], v[152:155], v[208:211], v[82:85]
	v_mfma_f32_16x16x32_bf16 v[110:113], v[156:159], v[172:175], v[110:113]
	v_mfma_f32_16x16x32_bf16 v[102:105], v[164:167], v[172:175], v[102:105]
	v_mfma_f32_16x16x32_bf16 v[94:97], v[156:159], v[180:183], v[94:97]
	v_mfma_f32_16x16x32_bf16 v[86:89], v[164:167], v[180:183], v[86:89]
	v_mfma_f32_16x16x32_bf16 v[78:81], v[156:159], v[188:191], v[78:81]
	v_mfma_f32_16x16x32_bf16 v[74:77], v[164:167], v[188:191], v[74:77]
	v_mfma_f32_16x16x32_bf16 v[70:73], v[156:159], v[196:199], v[70:73]
	v_mfma_f32_16x16x32_bf16 v[66:69], v[164:167], v[196:199], v[66:69]
	v_mfma_f32_16x16x32_bf16 v[110:113], v[160:163], v[176:179], v[110:113]
	v_mfma_f32_16x16x32_bf16 v[102:105], v[168:171], v[176:179], v[102:105]
	v_mfma_f32_16x16x32_bf16 v[94:97], v[160:163], v[184:187], v[94:97]
	v_mfma_f32_16x16x32_bf16 v[86:89], v[168:171], v[184:187], v[86:89]
	v_mfma_f32_16x16x32_bf16 v[78:81], v[160:163], v[192:195], v[78:81]
	v_mfma_f32_16x16x32_bf16 v[74:77], v[168:171], v[192:195], v[74:77]
	v_mfma_f32_16x16x32_bf16 v[70:73], v[160:163], v[208:211], v[70:73]
	v_mfma_f32_16x16x32_bf16 v[66:69], v[168:171], v[208:211], v[66:69]
	s_barrier
	s_setprio 0
	s_add_i32 s0, s33, s26
	s_mov_b32 m0, s0
	ds_read_b128 v[172:175], v139 offset:16384
	ds_read_b128 v[176:179], v139 offset:17408
	ds_read_b128 v[180:183], v139 offset:18432
	ds_read_b128 v[184:187], v139 offset:19456
	ds_read_b128 v[188:191], v139 offset:20480
	ds_read_b128 v[192:195], v139 offset:21504
	ds_read_b128 v[196:199], v139 offset:22528
	ds_read_b128 v[208:211], v139 offset:23552
	global_load_lds_dwordx4 v202, s[20:21]
	s_add_i32 m0, s0, 0x2000
	s_add_u32 s0, s20, 0x100000
	s_addc_u32 s1, s21, 0
	s_add_i32 s33, s55, s26
	global_load_lds_dwordx4 v130, s[20:21]
	s_mov_b32 m0, s33
	s_nop 0
	global_load_lds_dwordx4 v202, s[0:1]
	s_add_i32 m0, s33, 0x2000
	s_nop 0
	global_load_lds_dwordx4 v130, s[0:1]
	s_mov_b32 m0, s27
	s_nop 0
	global_load_lds_dwordx4 v202, s[22:23]
	s_mov_b32 m0, s28
	s_nop 0
	global_load_lds_dwordx4 v130, s[22:23]
	s_waitcnt vmcnt(8)
	s_waitcnt lgkmcnt(0)
	s_setprio 1
	s_barrier
	v_mfma_f32_16x16x32_bf16 v[62:65], v[140:143], v[172:175], v[62:65]
	v_mfma_f32_16x16x32_bf16 v[58:61], v[148:151], v[172:175], v[58:61]
	v_mfma_f32_16x16x32_bf16 v[54:57], v[140:143], v[180:183], v[54:57]
	v_mfma_f32_16x16x32_bf16 v[50:53], v[148:151], v[180:183], v[50:53]
	v_mfma_f32_16x16x32_bf16 v[38:41], v[140:143], v[188:191], v[38:41]
	v_mfma_f32_16x16x32_bf16 v[34:37], v[148:151], v[188:191], v[34:37]
	v_mfma_f32_16x16x32_bf16 v[22:25], v[140:143], v[196:199], v[22:25]
	v_mfma_f32_16x16x32_bf16 v[18:21], v[148:151], v[196:199], v[18:21]
	v_mfma_f32_16x16x32_bf16 v[62:65], v[144:147], v[176:179], v[62:65]
	v_mfma_f32_16x16x32_bf16 v[58:61], v[152:155], v[176:179], v[58:61]
	v_mfma_f32_16x16x32_bf16 v[54:57], v[144:147], v[184:187], v[54:57]
	v_mfma_f32_16x16x32_bf16 v[50:53], v[152:155], v[184:187], v[50:53]
	v_mfma_f32_16x16x32_bf16 v[38:41], v[144:147], v[192:195], v[38:41]
	v_mfma_f32_16x16x32_bf16 v[34:37], v[152:155], v[192:195], v[34:37]
	v_mfma_f32_16x16x32_bf16 v[22:25], v[144:147], v[208:211], v[22:25]
	v_mfma_f32_16x16x32_bf16 v[18:21], v[152:155], v[208:211], v[18:21]
	v_mfma_f32_16x16x32_bf16 v[46:49], v[156:159], v[172:175], v[46:49]
	v_mfma_f32_16x16x32_bf16 v[42:45], v[164:167], v[172:175], v[42:45]
	v_mfma_f32_16x16x32_bf16 v[30:33], v[156:159], v[180:183], v[30:33]
	v_mfma_f32_16x16x32_bf16 v[26:29], v[164:167], v[180:183], v[26:29]
	v_mfma_f32_16x16x32_bf16 v[14:17], v[156:159], v[188:191], v[14:17]
	v_mfma_f32_16x16x32_bf16 v[10:13], v[164:167], v[188:191], v[10:13]
	v_mfma_f32_16x16x32_bf16 v[6:9], v[156:159], v[196:199], v[6:9]
	v_mfma_f32_16x16x32_bf16 v[2:5], v[164:167], v[196:199], v[2:5]
	v_mfma_f32_16x16x32_bf16 v[46:49], v[160:163], v[176:179], v[46:49]
	v_mfma_f32_16x16x32_bf16 v[42:45], v[168:171], v[176:179], v[42:45]
	v_mfma_f32_16x16x32_bf16 v[30:33], v[160:163], v[184:187], v[30:33]
	v_mfma_f32_16x16x32_bf16 v[26:29], v[168:171], v[184:187], v[26:29]
	v_mfma_f32_16x16x32_bf16 v[14:17], v[160:163], v[192:195], v[14:17]
	v_mfma_f32_16x16x32_bf16 v[10:13], v[168:171], v[192:195], v[10:13]
	v_mfma_f32_16x16x32_bf16 v[6:9], v[160:163], v[208:211], v[6:9]
	v_mfma_f32_16x16x32_bf16 v[2:5], v[168:171], v[208:211], v[2:5]
	s_barrier
	s_setprio 0
	s_add_i32 s33, 0, 0x18000
	s_add_i32 s55, 0, 0x1c000
	ds_read_b128 v[140:143], v136 offset:32768
	ds_read_b128 v[144:147], v136 offset:33792
	ds_read_b128 v[148:151], v136 offset:34816
	ds_read_b128 v[152:155], v136 offset:35840
	ds_read_b128 v[156:159], v136 offset:49152
	ds_read_b128 v[160:163], v136 offset:50176
	ds_read_b128 v[164:167], v136 offset:51200
	ds_read_b128 v[168:171], v136 offset:52224
	s_add_u32 s0, s22, 0x100000
	s_addc_u32 s1, s23, 0
	s_mov_b32 m0, s29
	ds_read_b128 v[172:175], v139 offset:32768
	ds_read_b128 v[176:179], v139 offset:33792
	ds_read_b128 v[180:183], v139 offset:34816
	ds_read_b128 v[184:187], v139 offset:35840
	ds_read_b128 v[188:191], v139 offset:36864
	ds_read_b128 v[192:195], v139 offset:37888
	ds_read_b128 v[196:199], v139 offset:38912
	ds_read_b128 v[208:211], v139 offset:39936
	global_load_lds_dwordx4 v202, s[0:1]
	s_mov_b32 m0, s30
	s_nop 0
	global_load_lds_dwordx4 v130, s[0:1]
	s_waitcnt vmcnt(8)
	s_waitcnt lgkmcnt(0)
	s_setprio 1
	s_barrier
	v_mfma_f32_16x16x32_bf16 v[126:129], v[140:143], v[172:175], v[126:129]
	v_mfma_f32_16x16x32_bf16 v[122:125], v[148:151], v[172:175], v[122:125]
	v_mfma_f32_16x16x32_bf16 v[118:121], v[140:143], v[180:183], v[118:121]
	v_mfma_f32_16x16x32_bf16 v[114:117], v[148:151], v[180:183], v[114:117]
	v_mfma_f32_16x16x32_bf16 v[106:109], v[140:143], v[188:191], v[106:109]
	v_mfma_f32_16x16x32_bf16 v[98:101], v[148:151], v[188:191], v[98:101]
	v_mfma_f32_16x16x32_bf16 v[90:93], v[140:143], v[196:199], v[90:93]
	v_mfma_f32_16x16x32_bf16 v[82:85], v[148:151], v[196:199], v[82:85]
	v_mfma_f32_16x16x32_bf16 v[126:129], v[144:147], v[176:179], v[126:129]
	v_mfma_f32_16x16x32_bf16 v[122:125], v[152:155], v[176:179], v[122:125]
	v_mfma_f32_16x16x32_bf16 v[118:121], v[144:147], v[184:187], v[118:121]
	v_mfma_f32_16x16x32_bf16 v[114:117], v[152:155], v[184:187], v[114:117]
	v_mfma_f32_16x16x32_bf16 v[106:109], v[144:147], v[192:195], v[106:109]
	v_mfma_f32_16x16x32_bf16 v[98:101], v[152:155], v[192:195], v[98:101]
	v_mfma_f32_16x16x32_bf16 v[90:93], v[144:147], v[208:211], v[90:93]
	v_mfma_f32_16x16x32_bf16 v[82:85], v[152:155], v[208:211], v[82:85]
	v_mfma_f32_16x16x32_bf16 v[110:113], v[156:159], v[172:175], v[110:113]
	v_mfma_f32_16x16x32_bf16 v[102:105], v[164:167], v[172:175], v[102:105]
	v_mfma_f32_16x16x32_bf16 v[94:97], v[156:159], v[180:183], v[94:97]
	v_mfma_f32_16x16x32_bf16 v[86:89], v[164:167], v[180:183], v[86:89]
	v_mfma_f32_16x16x32_bf16 v[78:81], v[156:159], v[188:191], v[78:81]
	v_mfma_f32_16x16x32_bf16 v[74:77], v[164:167], v[188:191], v[74:77]
	v_mfma_f32_16x16x32_bf16 v[70:73], v[156:159], v[196:199], v[70:73]
	v_mfma_f32_16x16x32_bf16 v[66:69], v[164:167], v[196:199], v[66:69]
	v_mfma_f32_16x16x32_bf16 v[110:113], v[160:163], v[176:179], v[110:113]
	v_mfma_f32_16x16x32_bf16 v[102:105], v[168:171], v[176:179], v[102:105]
	v_mfma_f32_16x16x32_bf16 v[94:97], v[160:163], v[184:187], v[94:97]
	v_mfma_f32_16x16x32_bf16 v[86:89], v[168:171], v[184:187], v[86:89]
	v_mfma_f32_16x16x32_bf16 v[78:81], v[160:163], v[192:195], v[78:81]
	v_mfma_f32_16x16x32_bf16 v[74:77], v[168:171], v[192:195], v[74:77]
	v_mfma_f32_16x16x32_bf16 v[70:73], v[160:163], v[208:211], v[70:73]
	v_mfma_f32_16x16x32_bf16 v[66:69], v[168:171], v[208:211], v[66:69]
	s_barrier
	s_setprio 0
	s_add_i32 s0, s33, s26
	s_add_u32 s100, s20, 0x80
	s_addc_u32 s101, s21, 0
	s_mov_b32 m0, s0
	ds_read_b128 v[172:175], v139 offset:49152
	ds_read_b128 v[176:179], v139 offset:50176
	ds_read_b128 v[180:183], v139 offset:51200
	ds_read_b128 v[184:187], v139 offset:52224
	ds_read_b128 v[188:191], v139 offset:53248
	ds_read_b128 v[192:195], v139 offset:54272
	ds_read_b128 v[196:199], v139 offset:55296
	ds_read_b128 v[208:211], v139 offset:56320
	global_load_lds_dwordx4 v202, s[100:101]
	s_add_i32 m0, s0, 0x2000
	s_add_u32 s100, s20, 0x80
	s_addc_u32 s101, s21, 0
	s_add_u32 s0, s20, 0x100080
	s_addc_u32 s1, s21, 0
	s_add_i32 s20, s55, s26
	global_load_lds_dwordx4 v130, s[100:101]
	s_mov_b32 m0, s20
	s_nop 0
	global_load_lds_dwordx4 v202, s[0:1]
	s_add_i32 m0, s20, 0x2000
	s_nop 0
	global_load_lds_dwordx4 v130, s[0:1]
	s_add_u32 s100, s22, 0x80
	s_addc_u32 s101, s23, 0
	s_mov_b32 m0, s31
	s_nop 0
	global_load_lds_dwordx4 v202, s[100:101]
	s_add_u32 s100, s22, 0x80
	s_addc_u32 s101, s23, 0
	s_mov_b32 m0, s34
	s_nop 0
	global_load_lds_dwordx4 v130, s[100:101]
	s_add_i32 s49, s49, 2
	s_add_u32 s18, s18, 0x100
	s_addc_u32 s19, s19, 0
	s_add_u32 s9, s9, 0x100
	s_addc_u32 s11, s11, 0
	s_waitcnt vmcnt(8)
	s_waitcnt lgkmcnt(0)
	s_setprio 1
	s_barrier
	v_mfma_f32_16x16x32_bf16 v[62:65], v[140:143], v[172:175], v[62:65]
	v_mfma_f32_16x16x32_bf16 v[58:61], v[148:151], v[172:175], v[58:61]
	v_mfma_f32_16x16x32_bf16 v[54:57], v[140:143], v[180:183], v[54:57]
	v_mfma_f32_16x16x32_bf16 v[50:53], v[148:151], v[180:183], v[50:53]
	v_mfma_f32_16x16x32_bf16 v[38:41], v[140:143], v[188:191], v[38:41]
	v_mfma_f32_16x16x32_bf16 v[34:37], v[148:151], v[188:191], v[34:37]
	v_mfma_f32_16x16x32_bf16 v[22:25], v[140:143], v[196:199], v[22:25]
	v_mfma_f32_16x16x32_bf16 v[18:21], v[148:151], v[196:199], v[18:21]
	v_mfma_f32_16x16x32_bf16 v[62:65], v[144:147], v[176:179], v[62:65]
	v_mfma_f32_16x16x32_bf16 v[58:61], v[152:155], v[176:179], v[58:61]
	v_mfma_f32_16x16x32_bf16 v[54:57], v[144:147], v[184:187], v[54:57]
	v_mfma_f32_16x16x32_bf16 v[50:53], v[152:155], v[184:187], v[50:53]
	v_mfma_f32_16x16x32_bf16 v[38:41], v[144:147], v[192:195], v[38:41]
	v_mfma_f32_16x16x32_bf16 v[34:37], v[152:155], v[192:195], v[34:37]
	v_mfma_f32_16x16x32_bf16 v[22:25], v[144:147], v[208:211], v[22:25]
	v_mfma_f32_16x16x32_bf16 v[18:21], v[152:155], v[208:211], v[18:21]
	v_mfma_f32_16x16x32_bf16 v[46:49], v[156:159], v[172:175], v[46:49]
	v_mfma_f32_16x16x32_bf16 v[42:45], v[164:167], v[172:175], v[42:45]
	v_mfma_f32_16x16x32_bf16 v[30:33], v[156:159], v[180:183], v[30:33]
	v_mfma_f32_16x16x32_bf16 v[26:29], v[164:167], v[180:183], v[26:29]
	v_mfma_f32_16x16x32_bf16 v[14:17], v[156:159], v[188:191], v[14:17]
	v_mfma_f32_16x16x32_bf16 v[10:13], v[164:167], v[188:191], v[10:13]
	v_mfma_f32_16x16x32_bf16 v[6:9], v[156:159], v[196:199], v[6:9]
	v_mfma_f32_16x16x32_bf16 v[2:5], v[164:167], v[196:199], v[2:5]
	v_mfma_f32_16x16x32_bf16 v[46:49], v[160:163], v[176:179], v[46:49]
	v_mfma_f32_16x16x32_bf16 v[42:45], v[168:171], v[176:179], v[42:45]
	v_mfma_f32_16x16x32_bf16 v[30:33], v[160:163], v[184:187], v[30:33]
	v_mfma_f32_16x16x32_bf16 v[26:29], v[168:171], v[184:187], v[26:29]
	v_mfma_f32_16x16x32_bf16 v[14:17], v[160:163], v[192:195], v[14:17]
	v_mfma_f32_16x16x32_bf16 v[10:13], v[168:171], v[192:195], v[10:13]
	v_mfma_f32_16x16x32_bf16 v[6:9], v[160:163], v[208:211], v[6:9]
	v_mfma_f32_16x16x32_bf16 v[2:5], v[168:171], v[208:211], v[2:5]
	s_barrier
	s_setprio 0
	s_cmp_gt_u32 s49, 5
	s_cbranch_scc0 .LBB0_712
	s_and_b64 vcc, exec, s[6:7]
	s_cbranch_vccz .LBB0_715
	s_barrier

.Lpeel_mid_3:
	s_add_i32 s33, 0, 0x18000
	s_add_i32 s55, 0, 0x1c000
	ds_read_b128 v[146:149], v143 offset:32768
	ds_read_b128 v[150:153], v143 offset:33792
	ds_read_b128 v[154:157], v143 offset:34816
	ds_read_b128 v[158:161], v143 offset:35840
	ds_read_b128 v[162:165], v143 offset:49152
	ds_read_b128 v[166:169], v143 offset:50176
	ds_read_b128 v[170:173], v143 offset:51200
	ds_read_b128 v[174:177], v143 offset:52224
	s_add_u32 s0, s22, 0x80000
	s_addc_u32 s1, s23, 0
	s_mov_b32 m0, s29
	ds_read_b128 v[178:181], v145 offset:32768
	ds_read_b128 v[182:185], v145 offset:33792
	ds_read_b128 v[186:189], v145 offset:34816
	ds_read_b128 v[190:193], v145 offset:35840
	ds_read_b128 v[194:197], v145 offset:36864
	ds_read_b128 v[198:201], v145 offset:37888
	ds_read_b128 v[208:211], v145 offset:38912
	ds_read_b128 v[212:215], v145 offset:39936
	global_load_lds_dwordx4 v134, s[0:1]
	s_mov_b32 m0, s30
	s_nop 0
	global_load_lds_dwordx4 v132, s[0:1]
	s_waitcnt vmcnt(8)
	s_waitcnt lgkmcnt(0)
	s_setprio 1
	s_barrier
	v_mfma_f32_16x16x32_bf16 v[126:129], v[146:149], v[178:181], v[126:129]
	v_mfma_f32_16x16x32_bf16 v[118:121], v[154:157], v[178:181], v[118:121]
	v_mfma_f32_16x16x32_bf16 v[110:113], v[146:149], v[186:189], v[110:113]
	v_mfma_f32_16x16x32_bf16 v[102:105], v[154:157], v[186:189], v[102:105]
	v_mfma_f32_16x16x32_bf16 v[94:97], v[146:149], v[194:197], v[94:97]
	v_mfma_f32_16x16x32_bf16 v[86:89], v[154:157], v[194:197], v[86:89]
	v_mfma_f32_16x16x32_bf16 v[78:81], v[146:149], v[208:211], v[78:81]
	v_mfma_f32_16x16x32_bf16 v[70:73], v[154:157], v[208:211], v[70:73]
	v_mfma_f32_16x16x32_bf16 v[126:129], v[150:153], v[182:185], v[126:129]
	v_mfma_f32_16x16x32_bf16 v[118:121], v[158:161], v[182:185], v[118:121]
	v_mfma_f32_16x16x32_bf16 v[110:113], v[150:153], v[190:193], v[110:113]
	v_mfma_f32_16x16x32_bf16 v[102:105], v[158:161], v[190:193], v[102:105]
	v_mfma_f32_16x16x32_bf16 v[94:97], v[150:153], v[198:201], v[94:97]
	v_mfma_f32_16x16x32_bf16 v[86:89], v[158:161], v[198:201], v[86:89]
	v_mfma_f32_16x16x32_bf16 v[78:81], v[150:153], v[212:215], v[78:81]
	v_mfma_f32_16x16x32_bf16 v[70:73], v[158:161], v[212:215], v[70:73]
	v_mfma_f32_16x16x32_bf16 v[122:125], v[162:165], v[178:181], v[122:125]
	v_mfma_f32_16x16x32_bf16 v[114:117], v[170:173], v[178:181], v[114:117]
	v_mfma_f32_16x16x32_bf16 v[106:109], v[162:165], v[186:189], v[106:109]
	v_mfma_f32_16x16x32_bf16 v[98:101], v[170:173], v[186:189], v[98:101]
	v_mfma_f32_16x16x32_bf16 v[90:93], v[162:165], v[194:197], v[90:93]
	v_mfma_f32_16x16x32_bf16 v[82:85], v[170:173], v[194:197], v[82:85]
	v_mfma_f32_16x16x32_bf16 v[74:77], v[162:165], v[208:211], v[74:77]
	v_mfma_f32_16x16x32_bf16 v[66:69], v[170:173], v[208:211], v[66:69]
	v_mfma_f32_16x16x32_bf16 v[122:125], v[166:169], v[182:185], v[122:125]
	v_mfma_f32_16x16x32_bf16 v[114:117], v[174:177], v[182:185], v[114:117]
	v_mfma_f32_16x16x32_bf16 v[106:109], v[166:169], v[190:193], v[106:109]
	v_mfma_f32_16x16x32_bf16 v[98:101], v[174:177], v[190:193], v[98:101]
	v_mfma_f32_16x16x32_bf16 v[90:93], v[166:169], v[198:201], v[90:93]
	v_mfma_f32_16x16x32_bf16 v[82:85], v[174:177], v[198:201], v[82:85]
	v_mfma_f32_16x16x32_bf16 v[74:77], v[166:169], v[212:215], v[74:77]
	v_mfma_f32_16x16x32_bf16 v[66:69], v[174:177], v[212:215], v[66:69]
	s_barrier
	s_setprio 0
	s_add_i32 s0, s33, s26
	s_add_u32 s100, s20, 0x80
	s_addc_u32 s101, s21, 0
	s_mov_b32 m0, s0
	ds_read_b128 v[178:181], v145 offset:49152
	ds_read_b128 v[182:185], v145 offset:50176
	ds_read_b128 v[186:189], v145 offset:51200
	ds_read_b128 v[190:193], v145 offset:52224
	ds_read_b128 v[194:197], v145 offset:53248
	ds_read_b128 v[198:201], v145 offset:54272
	ds_read_b128 v[208:211], v145 offset:55296
	ds_read_b128 v[212:215], v145 offset:56320
	global_load_lds_dwordx4 v202, s[100:101]
	s_add_i32 m0, s0, 0x2000
	s_add_u32 s100, s20, 0x80
	s_addc_u32 s101, s21, 0
	s_add_u32 s0, s20, 0x80080
	s_addc_u32 s1, s21, 0
	s_add_i32 s20, s55, s26
	global_load_lds_dwordx4 v130, s[100:101]
	s_mov_b32 m0, s20
	s_nop 0
	global_load_lds_dwordx4 v202, s[0:1]
	s_add_i32 m0, s20, 0x2000
	s_nop 0
	global_load_lds_dwordx4 v130, s[0:1]
	s_add_u32 s100, s22, 0x80
	s_addc_u32 s101, s23, 0
	s_mov_b32 m0, s31
	s_nop 0
	global_load_lds_dwordx4 v134, s[100:101]
	s_add_u32 s100, s22, 0x80
	s_addc_u32 s101, s23, 0
	s_mov_b32 m0, s34
	s_nop 0
	global_load_lds_dwordx4 v132, s[100:101]
	s_add_i32 s59, s59, 2
	s_add_u32 s18, s18, 0x100
	s_addc_u32 s19, s19, 0
	s_add_u32 s49, s49, 0x100
	s_addc_u32 s58, s58, 0
	s_waitcnt vmcnt(8)
	s_waitcnt lgkmcnt(0)
	s_setprio 1
	s_barrier
	v_mfma_f32_16x16x32_bf16 v[62:65], v[146:149], v[178:181], v[62:65]
	v_mfma_f32_16x16x32_bf16 v[54:57], v[154:157], v[178:181], v[54:57]
	v_mfma_f32_16x16x32_bf16 v[46:49], v[146:149], v[186:189], v[46:49]
	v_mfma_f32_16x16x32_bf16 v[38:41], v[154:157], v[186:189], v[38:41]
	v_mfma_f32_16x16x32_bf16 v[30:33], v[146:149], v[194:197], v[30:33]
	v_mfma_f32_16x16x32_bf16 v[22:25], v[154:157], v[194:197], v[22:25]
	v_mfma_f32_16x16x32_bf16 v[14:17], v[146:149], v[208:211], v[14:17]
	v_mfma_f32_16x16x32_bf16 v[6:9], v[154:157], v[208:211], v[6:9]
	v_mfma_f32_16x16x32_bf16 v[62:65], v[150:153], v[182:185], v[62:65]
	v_mfma_f32_16x16x32_bf16 v[54:57], v[158:161], v[182:185], v[54:57]
	v_mfma_f32_16x16x32_bf16 v[46:49], v[150:153], v[190:193], v[46:49]
	v_mfma_f32_16x16x32_bf16 v[38:41], v[158:161], v[190:193], v[38:41]
	v_mfma_f32_16x16x32_bf16 v[30:33], v[150:153], v[198:201], v[30:33]
	v_mfma_f32_16x16x32_bf16 v[22:25], v[158:161], v[198:201], v[22:25]
	v_mfma_f32_16x16x32_bf16 v[14:17], v[150:153], v[212:215], v[14:17]
	v_mfma_f32_16x16x32_bf16 v[6:9], v[158:161], v[212:215], v[6:9]
	v_mfma_f32_16x16x32_bf16 v[58:61], v[162:165], v[178:181], v[58:61]
	v_mfma_f32_16x16x32_bf16 v[50:53], v[170:173], v[178:181], v[50:53]
	v_mfma_f32_16x16x32_bf16 v[42:45], v[162:165], v[186:189], v[42:45]
	v_mfma_f32_16x16x32_bf16 v[34:37], v[170:173], v[186:189], v[34:37]
	v_mfma_f32_16x16x32_bf16 v[26:29], v[162:165], v[194:197], v[26:29]
	v_mfma_f32_16x16x32_bf16 v[18:21], v[170:173], v[194:197], v[18:21]
	v_mfma_f32_16x16x32_bf16 v[10:13], v[162:165], v[208:211], v[10:13]
	v_mfma_f32_16x16x32_bf16 v[2:5], v[170:173], v[208:211], v[2:5]
	v_mfma_f32_16x16x32_bf16 v[58:61], v[166:169], v[182:185], v[58:61]
	v_mfma_f32_16x16x32_bf16 v[50:53], v[174:177], v[182:185], v[50:53]
	v_mfma_f32_16x16x32_bf16 v[42:45], v[166:169], v[190:193], v[42:45]
	v_mfma_f32_16x16x32_bf16 v[34:37], v[174:177], v[190:193], v[34:37]
	v_mfma_f32_16x16x32_bf16 v[26:29], v[166:169], v[198:201], v[26:29]
	v_mfma_f32_16x16x32_bf16 v[18:21], v[174:177], v[198:201], v[18:21]
	v_mfma_f32_16x16x32_bf16 v[10:13], v[166:169], v[212:215], v[10:13]
	v_mfma_f32_16x16x32_bf16 v[2:5], v[174:177], v[212:215], v[2:5]
	s_barrier
	s_setprio 0
	s_cmp_gt_u32 s59, 29
	s_cbranch_scc0 .LBB0_837
	s_mov_b32 s101, 0x80000001
	s_and_b64 vcc, exec, s[6:7]
	s_cbranch_vccz .LBB0_840
	s_barrier

.LBB0_1115:
	s_add_u32 s0, s22, 0xfff80080
	s_addc_u32 s1, s23, -1
	s_add_i32 s33, 0, 0x10000
	s_cmp_eq_u32 s58, 28
	s_cselect_b32 s5, s17, s1
	s_cselect_b32 s4, s39, s0
	s_cselect_b32 s3, s15, s49
	s_cselect_b32 s2, s40, s41
	s_add_i32 s55, 0, 0x14000
	ds_read_b128 v[148:151], v145
	ds_read_b128 v[152:155], v145 offset:1024
	ds_read_b128 v[156:159], v145 offset:2048
	ds_read_b128 v[160:163], v145 offset:3072
	ds_read_b128 v[164:167], v145 offset:16384
	ds_read_b128 v[168:171], v145 offset:17408
	ds_read_b128 v[172:175], v145 offset:18432
	ds_read_b128 v[176:179], v145 offset:19456
	s_add_i32 m0, s27, 0xc000
	ds_read_b128 v[180:183], v147
	ds_read_b128 v[184:187], v147 offset:1024
	ds_read_b128 v[188:191], v147 offset:2048
	ds_read_b128 v[192:195], v147 offset:3072
	ds_read_b128 v[196:199], v147 offset:4096
	ds_read_b128 v[208:211], v147 offset:5120
	ds_read_b128 v[212:215], v147 offset:6144
	ds_read_b128 v[216:219], v147 offset:7168
	global_load_lds_dwordx4 v138, s[22:23]
	s_add_i32 m0, s27, 0xe000
	s_nop 0
	global_load_lds_dwordx4 v140, s[22:23]
	s_waitcnt vmcnt(8)
	s_waitcnt lgkmcnt(0)
	s_setprio 1
	s_barrier
	v_mfma_f32_16x16x32_bf16 v[126:129], v[148:151], v[180:183], v[126:129]
	v_mfma_f32_16x16x32_bf16 v[122:125], v[156:159], v[180:183], v[122:125]
	v_mfma_f32_16x16x32_bf16 v[110:113], v[148:151], v[188:191], v[110:113]
	v_mfma_f32_16x16x32_bf16 v[106:109], v[156:159], v[188:191], v[106:109]
	v_mfma_f32_16x16x32_bf16 v[94:97], v[148:151], v[196:199], v[94:97]
	v_mfma_f32_16x16x32_bf16 v[90:93], v[156:159], v[196:199], v[90:93]
	v_mfma_f32_16x16x32_bf16 v[78:81], v[148:151], v[212:215], v[78:81]
	v_mfma_f32_16x16x32_bf16 v[74:77], v[156:159], v[212:215], v[74:77]
	v_mfma_f32_16x16x32_bf16 v[126:129], v[152:155], v[184:187], v[126:129]
	v_mfma_f32_16x16x32_bf16 v[122:125], v[160:163], v[184:187], v[122:125]
	v_mfma_f32_16x16x32_bf16 v[110:113], v[152:155], v[192:195], v[110:113]
	v_mfma_f32_16x16x32_bf16 v[106:109], v[160:163], v[192:195], v[106:109]
	v_mfma_f32_16x16x32_bf16 v[94:97], v[152:155], v[208:211], v[94:97]
	v_mfma_f32_16x16x32_bf16 v[90:93], v[160:163], v[208:211], v[90:93]
	v_mfma_f32_16x16x32_bf16 v[78:81], v[152:155], v[216:219], v[78:81]
	v_mfma_f32_16x16x32_bf16 v[74:77], v[160:163], v[216:219], v[74:77]
	v_mfma_f32_16x16x32_bf16 v[118:121], v[164:167], v[180:183], v[118:121]
	v_mfma_f32_16x16x32_bf16 v[114:117], v[172:175], v[180:183], v[114:117]
	v_mfma_f32_16x16x32_bf16 v[102:105], v[164:167], v[188:191], v[102:105]
	v_mfma_f32_16x16x32_bf16 v[98:101], v[172:175], v[188:191], v[98:101]
	v_mfma_f32_16x16x32_bf16 v[86:89], v[164:167], v[196:199], v[86:89]
	v_mfma_f32_16x16x32_bf16 v[82:85], v[172:175], v[196:199], v[82:85]
	v_mfma_f32_16x16x32_bf16 v[70:73], v[164:167], v[212:215], v[70:73]
	v_mfma_f32_16x16x32_bf16 v[66:69], v[172:175], v[212:215], v[66:69]
	v_mfma_f32_16x16x32_bf16 v[118:121], v[168:171], v[184:187], v[118:121]
	v_mfma_f32_16x16x32_bf16 v[114:117], v[176:179], v[184:187], v[114:117]
	v_mfma_f32_16x16x32_bf16 v[102:105], v[168:171], v[192:195], v[102:105]
	v_mfma_f32_16x16x32_bf16 v[98:101], v[176:179], v[192:195], v[98:101]
	v_mfma_f32_16x16x32_bf16 v[86:89], v[168:171], v[208:211], v[86:89]
	v_mfma_f32_16x16x32_bf16 v[82:85], v[176:179], v[208:211], v[82:85]
	v_mfma_f32_16x16x32_bf16 v[70:73], v[168:171], v[216:219], v[70:73]
	v_mfma_f32_16x16x32_bf16 v[66:69], v[176:179], v[216:219], v[66:69]
	s_barrier
	s_setprio 0
	s_add_i32 s0, s33, s26
	s_mov_b32 m0, s0
	ds_read_b128 v[180:183], v147 offset:16384
	ds_read_b128 v[184:187], v147 offset:17408
	ds_read_b128 v[188:191], v147 offset:18432
	ds_read_b128 v[192:195], v147 offset:19456
	ds_read_b128 v[196:199], v147 offset:20480
	ds_read_b128 v[208:211], v147 offset:21504
	ds_read_b128 v[212:215], v147 offset:22528
	ds_read_b128 v[216:219], v147 offset:23552
	global_load_lds_dwordx4 v134, s[2:3]
	s_add_i32 m0, s0, 0x2000
	s_add_u32 s0, s2, 0x80000
	s_addc_u32 s1, s3, 0
	s_add_i32 s33, s55, s26
	global_load_lds_dwordx4 v130, s[2:3]
	s_mov_b32 m0, s33
	s_nop 0
	global_load_lds_dwordx4 v134, s[0:1]
	s_add_i32 m0, s33, 0x2000
	s_nop 0
	global_load_lds_dwordx4 v130, s[0:1]
	s_mov_b32 m0, s27
	s_nop 0
	global_load_lds_dwordx4 v136, s[4:5]
	s_mov_b32 m0, s28
	s_nop 0
	global_load_lds_dwordx4 v132, s[4:5]
	s_waitcnt vmcnt(8)
	s_waitcnt lgkmcnt(0)
	s_setprio 1
	s_barrier
	v_mfma_f32_16x16x32_bf16 v[62:65], v[148:151], v[180:183], v[62:65]
	v_mfma_f32_16x16x32_bf16 v[58:61], v[156:159], v[180:183], v[58:61]
	v_mfma_f32_16x16x32_bf16 v[46:49], v[148:151], v[188:191], v[46:49]
	v_mfma_f32_16x16x32_bf16 v[42:45], v[156:159], v[188:191], v[42:45]
	v_mfma_f32_16x16x32_bf16 v[30:33], v[148:151], v[196:199], v[30:33]
	v_mfma_f32_16x16x32_bf16 v[26:29], v[156:159], v[196:199], v[26:29]
	v_mfma_f32_16x16x32_bf16 v[14:17], v[148:151], v[212:215], v[14:17]
	v_mfma_f32_16x16x32_bf16 v[10:13], v[156:159], v[212:215], v[10:13]
	v_mfma_f32_16x16x32_bf16 v[62:65], v[152:155], v[184:187], v[62:65]
	v_mfma_f32_16x16x32_bf16 v[58:61], v[160:163], v[184:187], v[58:61]
	v_mfma_f32_16x16x32_bf16 v[46:49], v[152:155], v[192:195], v[46:49]
	v_mfma_f32_16x16x32_bf16 v[42:45], v[160:163], v[192:195], v[42:45]
	v_mfma_f32_16x16x32_bf16 v[30:33], v[152:155], v[208:211], v[30:33]
	v_mfma_f32_16x16x32_bf16 v[26:29], v[160:163], v[208:211], v[26:29]
	v_mfma_f32_16x16x32_bf16 v[14:17], v[152:155], v[216:219], v[14:17]
	v_mfma_f32_16x16x32_bf16 v[10:13], v[160:163], v[216:219], v[10:13]
	v_mfma_f32_16x16x32_bf16 v[54:57], v[164:167], v[180:183], v[54:57]
	v_mfma_f32_16x16x32_bf16 v[50:53], v[172:175], v[180:183], v[50:53]
	v_mfma_f32_16x16x32_bf16 v[38:41], v[164:167], v[188:191], v[38:41]
	v_mfma_f32_16x16x32_bf16 v[34:37], v[172:175], v[188:191], v[34:37]
	v_mfma_f32_16x16x32_bf16 v[22:25], v[164:167], v[196:199], v[22:25]
	v_mfma_f32_16x16x32_bf16 v[18:21], v[172:175], v[196:199], v[18:21]
	v_mfma_f32_16x16x32_bf16 v[6:9], v[164:167], v[212:215], v[6:9]
	v_mfma_f32_16x16x32_bf16 v[2:5], v[172:175], v[212:215], v[2:5]
	v_mfma_f32_16x16x32_bf16 v[54:57], v[168:171], v[184:187], v[54:57]
	v_mfma_f32_16x16x32_bf16 v[50:53], v[176:179], v[184:187], v[50:53]
	v_mfma_f32_16x16x32_bf16 v[38:41], v[168:171], v[192:195], v[38:41]
	v_mfma_f32_16x16x32_bf16 v[34:37], v[176:179], v[192:195], v[34:37]
	v_mfma_f32_16x16x32_bf16 v[22:25], v[168:171], v[208:211], v[22:25]
	v_mfma_f32_16x16x32_bf16 v[18:21], v[176:179], v[208:211], v[18:21]
	v_mfma_f32_16x16x32_bf16 v[6:9], v[168:171], v[216:219], v[6:9]
	v_mfma_f32_16x16x32_bf16 v[2:5], v[176:179], v[216:219], v[2:5]
	s_barrier
	s_setprio 0
	s_add_i32 s33, 0, 0x18000
	s_add_i32 s55, 0, 0x1c000
	ds_read_b128 v[148:151], v145 offset:32768
	ds_read_b128 v[152:155], v145 offset:33792
	ds_read_b128 v[156:159], v145 offset:34816
	ds_read_b128 v[160:163], v145 offset:35840
	ds_read_b128 v[164:167], v145 offset:49152
	ds_read_b128 v[168:171], v145 offset:50176
	ds_read_b128 v[172:175], v145 offset:51200
	ds_read_b128 v[176:179], v145 offset:52224
	s_add_u32 s0, s4, 0x80000
	s_addc_u32 s1, s5, 0
	s_mov_b32 m0, s29
	ds_read_b128 v[180:183], v147 offset:32768
	ds_read_b128 v[184:187], v147 offset:33792
	ds_read_b128 v[188:191], v147 offset:34816
	ds_read_b128 v[192:195], v147 offset:35840
	ds_read_b128 v[196:199], v147 offset:36864
	ds_read_b128 v[208:211], v147 offset:37888
	ds_read_b128 v[212:215], v147 offset:38912
	ds_read_b128 v[216:219], v147 offset:39936
	global_load_lds_dwordx4 v136, s[0:1]
	s_mov_b32 m0, s30
	s_nop 0
	global_load_lds_dwordx4 v132, s[0:1]
	s_waitcnt vmcnt(8)
	s_waitcnt lgkmcnt(0)
	s_setprio 1
	s_barrier
	v_mfma_f32_16x16x32_bf16 v[126:129], v[148:151], v[180:183], v[126:129]
	v_mfma_f32_16x16x32_bf16 v[122:125], v[156:159], v[180:183], v[122:125]
	v_mfma_f32_16x16x32_bf16 v[110:113], v[148:151], v[188:191], v[110:113]
	v_mfma_f32_16x16x32_bf16 v[106:109], v[156:159], v[188:191], v[106:109]
	v_mfma_f32_16x16x32_bf16 v[94:97], v[148:151], v[196:199], v[94:97]
	v_mfma_f32_16x16x32_bf16 v[90:93], v[156:159], v[196:199], v[90:93]
	v_mfma_f32_16x16x32_bf16 v[78:81], v[148:151], v[212:215], v[78:81]
	v_mfma_f32_16x16x32_bf16 v[74:77], v[156:159], v[212:215], v[74:77]
	v_mfma_f32_16x16x32_bf16 v[126:129], v[152:155], v[184:187], v[126:129]
	v_mfma_f32_16x16x32_bf16 v[122:125], v[160:163], v[184:187], v[122:125]
	v_mfma_f32_16x16x32_bf16 v[110:113], v[152:155], v[192:195], v[110:113]
	v_mfma_f32_16x16x32_bf16 v[106:109], v[160:163], v[192:195], v[106:109]
	v_mfma_f32_16x16x32_bf16 v[94:97], v[152:155], v[208:211], v[94:97]
	v_mfma_f32_16x16x32_bf16 v[90:93], v[160:163], v[208:211], v[90:93]
	v_mfma_f32_16x16x32_bf16 v[78:81], v[152:155], v[216:219], v[78:81]
	v_mfma_f32_16x16x32_bf16 v[74:77], v[160:163], v[216:219], v[74:77]
	v_mfma_f32_16x16x32_bf16 v[118:121], v[164:167], v[180:183], v[118:121]
	v_mfma_f32_16x16x32_bf16 v[114:117], v[172:175], v[180:183], v[114:117]
	v_mfma_f32_16x16x32_bf16 v[102:105], v[164:167], v[188:191], v[102:105]
	v_mfma_f32_16x16x32_bf16 v[98:101], v[172:175], v[188:191], v[98:101]
	v_mfma_f32_16x16x32_bf16 v[86:89], v[164:167], v[196:199], v[86:89]
	v_mfma_f32_16x16x32_bf16 v[82:85], v[172:175], v[196:199], v[82:85]
	v_mfma_f32_16x16x32_bf16 v[70:73], v[164:167], v[212:215], v[70:73]
	v_mfma_f32_16x16x32_bf16 v[66:69], v[172:175], v[212:215], v[66:69]
	v_mfma_f32_16x16x32_bf16 v[118:121], v[168:171], v[184:187], v[118:121]
	v_mfma_f32_16x16x32_bf16 v[114:117], v[176:179], v[184:187], v[114:117]
	v_mfma_f32_16x16x32_bf16 v[102:105], v[168:171], v[192:195], v[102:105]
	v_mfma_f32_16x16x32_bf16 v[98:101], v[176:179], v[192:195], v[98:101]
	v_mfma_f32_16x16x32_bf16 v[86:89], v[168:171], v[208:211], v[86:89]
	v_mfma_f32_16x16x32_bf16 v[82:85], v[176:179], v[208:211], v[82:85]
	v_mfma_f32_16x16x32_bf16 v[70:73], v[168:171], v[216:219], v[70:73]
	v_mfma_f32_16x16x32_bf16 v[66:69], v[176:179], v[216:219], v[66:69]
	s_barrier
	s_setprio 0
	s_add_i32 s0, s33, s26
	s_add_u32 s100, s2, 0x80
	s_addc_u32 s101, s3, 0
	s_mov_b32 m0, s0
	ds_read_b128 v[180:183], v147 offset:49152
	ds_read_b128 v[184:187], v147 offset:50176
	ds_read_b128 v[188:191], v147 offset:51200
	ds_read_b128 v[192:195], v147 offset:52224
	ds_read_b128 v[196:199], v147 offset:53248
	ds_read_b128 v[208:211], v147 offset:54272
	ds_read_b128 v[212:215], v147 offset:55296
	ds_read_b128 v[216:219], v147 offset:56320
	global_load_lds_dwordx4 v134, s[100:101]
	s_add_i32 m0, s0, 0x2000
	s_add_u32 s100, s2, 0x80
	s_addc_u32 s101, s3, 0
	s_add_u32 s0, s2, 0x80080
	s_addc_u32 s1, s3, 0
	s_add_i32 s2, s55, s26
	global_load_lds_dwordx4 v130, s[100:101]
	s_mov_b32 m0, s2
	s_nop 0
	global_load_lds_dwordx4 v134, s[0:1]
	s_add_i32 m0, s2, 0x2000
	s_nop 0
	global_load_lds_dwordx4 v130, s[0:1]
	s_add_u32 s100, s4, 0x80
	s_addc_u32 s101, s5, 0
	s_mov_b32 m0, s34
	s_nop 0
	global_load_lds_dwordx4 v136, s[100:101]
	s_add_u32 s100, s4, 0x80
	s_addc_u32 s101, s5, 0
	s_mov_b32 m0, s35
	s_nop 0
	global_load_lds_dwordx4 v132, s[100:101]
	s_add_i32 s58, s58, 2
	s_add_u32 s22, s22, 0x100
	s_addc_u32 s23, s23, 0
	s_add_u32 s41, s41, 0x100
	s_addc_u32 s49, s49, 0
	s_waitcnt vmcnt(8)
	s_waitcnt lgkmcnt(0)
	s_setprio 1
	s_barrier
	v_mfma_f32_16x16x32_bf16 v[62:65], v[148:151], v[180:183], v[62:65]
	v_mfma_f32_16x16x32_bf16 v[58:61], v[156:159], v[180:183], v[58:61]
	v_mfma_f32_16x16x32_bf16 v[46:49], v[148:151], v[188:191], v[46:49]
	v_mfma_f32_16x16x32_bf16 v[42:45], v[156:159], v[188:191], v[42:45]
	v_mfma_f32_16x16x32_bf16 v[30:33], v[148:151], v[196:199], v[30:33]
	v_mfma_f32_16x16x32_bf16 v[26:29], v[156:159], v[196:199], v[26:29]
	v_mfma_f32_16x16x32_bf16 v[14:17], v[148:151], v[212:215], v[14:17]
	v_mfma_f32_16x16x32_bf16 v[10:13], v[156:159], v[212:215], v[10:13]
	v_mfma_f32_16x16x32_bf16 v[62:65], v[152:155], v[184:187], v[62:65]
	v_mfma_f32_16x16x32_bf16 v[58:61], v[160:163], v[184:187], v[58:61]
	v_mfma_f32_16x16x32_bf16 v[46:49], v[152:155], v[192:195], v[46:49]
	v_mfma_f32_16x16x32_bf16 v[42:45], v[160:163], v[192:195], v[42:45]
	v_mfma_f32_16x16x32_bf16 v[30:33], v[152:155], v[208:211], v[30:33]
	v_mfma_f32_16x16x32_bf16 v[26:29], v[160:163], v[208:211], v[26:29]
	v_mfma_f32_16x16x32_bf16 v[14:17], v[152:155], v[216:219], v[14:17]
	v_mfma_f32_16x16x32_bf16 v[10:13], v[160:163], v[216:219], v[10:13]
	v_mfma_f32_16x16x32_bf16 v[54:57], v[164:167], v[180:183], v[54:57]
	v_mfma_f32_16x16x32_bf16 v[50:53], v[172:175], v[180:183], v[50:53]
	v_mfma_f32_16x16x32_bf16 v[38:41], v[164:167], v[188:191], v[38:41]
	v_mfma_f32_16x16x32_bf16 v[34:37], v[172:175], v[188:191], v[34:37]
	v_mfma_f32_16x16x32_bf16 v[22:25], v[164:167], v[196:199], v[22:25]
	v_mfma_f32_16x16x32_bf16 v[18:21], v[172:175], v[196:199], v[18:21]
	v_mfma_f32_16x16x32_bf16 v[6:9], v[164:167], v[212:215], v[6:9]
	v_mfma_f32_16x16x32_bf16 v[2:5], v[172:175], v[212:215], v[2:5]
	v_mfma_f32_16x16x32_bf16 v[54:57], v[168:171], v[184:187], v[54:57]
	v_mfma_f32_16x16x32_bf16 v[50:53], v[176:179], v[184:187], v[50:53]
	v_mfma_f32_16x16x32_bf16 v[38:41], v[168:171], v[192:195], v[38:41]
	v_mfma_f32_16x16x32_bf16 v[34:37], v[176:179], v[192:195], v[34:37]
	v_mfma_f32_16x16x32_bf16 v[22:25], v[168:171], v[208:211], v[22:25]
	v_mfma_f32_16x16x32_bf16 v[18:21], v[176:179], v[208:211], v[18:21]
	v_mfma_f32_16x16x32_bf16 v[6:9], v[168:171], v[216:219], v[6:9]
	v_mfma_f32_16x16x32_bf16 v[2:5], v[176:179], v[216:219], v[2:5]
	s_barrier
	s_setprio 0
	s_cmp_gt_u32 s58, 29
	s_cbranch_scc0 .LBB0_1115
	s_and_b64 vcc, exec, s[10:11]
	s_cbranch_vccz .LBB0_1118
	s_barrier

.LBB0_1363:
	s_add_u32 s0, s20, 0xfffe0080
	s_addc_u32 s1, s21, -1
	s_add_i32 s33, 0, 0x10000
	s_cmp_eq_u32 s59, 4
	s_cselect_b32 s5, s38, s1
	s_cselect_b32 s4, s39, s0
	s_cselect_b32 s3, s40, s58
	s_cselect_b32 s2, s41, s49
	s_add_i32 s55, 0, 0x14000
	ds_read_b128 v[148:151], v143
	ds_read_b128 v[152:155], v143 offset:1024
	ds_read_b128 v[156:159], v143 offset:2048
	ds_read_b128 v[160:163], v143 offset:3072
	ds_read_b128 v[164:167], v143 offset:16384
	ds_read_b128 v[168:171], v143 offset:17408
	ds_read_b128 v[172:175], v143 offset:18432
	ds_read_b128 v[176:179], v143 offset:19456
	s_add_i32 m0, s25, 0xc000
	ds_read_b128 v[180:183], v146
	ds_read_b128 v[184:187], v146 offset:1024
	ds_read_b128 v[188:191], v146 offset:2048
	ds_read_b128 v[192:195], v146 offset:3072
	ds_read_b128 v[196:199], v146 offset:4096
	ds_read_b128 v[208:211], v146 offset:5120
	ds_read_b128 v[212:215], v146 offset:6144
	ds_read_b128 v[216:219], v146 offset:7168
	global_load_lds_dwordx4 v138, s[20:21]
	s_add_i32 m0, s25, 0xe000
	s_nop 0
	global_load_lds_dwordx4 v140, s[20:21]
	s_waitcnt vmcnt(8)
	s_waitcnt lgkmcnt(0)
	s_setprio 1
	s_barrier
	v_mfma_f32_16x16x32_bf16 v[126:129], v[148:151], v[180:183], v[126:129]
	v_mfma_f32_16x16x32_bf16 v[122:125], v[156:159], v[180:183], v[122:125]
	v_mfma_f32_16x16x32_bf16 v[110:113], v[148:151], v[188:191], v[110:113]
	v_mfma_f32_16x16x32_bf16 v[106:109], v[156:159], v[188:191], v[106:109]
	v_mfma_f32_16x16x32_bf16 v[94:97], v[148:151], v[196:199], v[94:97]
	v_mfma_f32_16x16x32_bf16 v[90:93], v[156:159], v[196:199], v[90:93]
	v_mfma_f32_16x16x32_bf16 v[78:81], v[148:151], v[212:215], v[78:81]
	v_mfma_f32_16x16x32_bf16 v[74:77], v[156:159], v[212:215], v[74:77]
	v_mfma_f32_16x16x32_bf16 v[126:129], v[152:155], v[184:187], v[126:129]
	v_mfma_f32_16x16x32_bf16 v[122:125], v[160:163], v[184:187], v[122:125]
	v_mfma_f32_16x16x32_bf16 v[110:113], v[152:155], v[192:195], v[110:113]
	v_mfma_f32_16x16x32_bf16 v[106:109], v[160:163], v[192:195], v[106:109]
	v_mfma_f32_16x16x32_bf16 v[94:97], v[152:155], v[208:211], v[94:97]
	v_mfma_f32_16x16x32_bf16 v[90:93], v[160:163], v[208:211], v[90:93]
	v_mfma_f32_16x16x32_bf16 v[78:81], v[152:155], v[216:219], v[78:81]
	v_mfma_f32_16x16x32_bf16 v[74:77], v[160:163], v[216:219], v[74:77]
	v_mfma_f32_16x16x32_bf16 v[118:121], v[164:167], v[180:183], v[118:121]
	v_mfma_f32_16x16x32_bf16 v[114:117], v[172:175], v[180:183], v[114:117]
	v_mfma_f32_16x16x32_bf16 v[102:105], v[164:167], v[188:191], v[102:105]
	v_mfma_f32_16x16x32_bf16 v[98:101], v[172:175], v[188:191], v[98:101]
	v_mfma_f32_16x16x32_bf16 v[86:89], v[164:167], v[196:199], v[86:89]
	v_mfma_f32_16x16x32_bf16 v[82:85], v[172:175], v[196:199], v[82:85]
	v_mfma_f32_16x16x32_bf16 v[70:73], v[164:167], v[212:215], v[70:73]
	v_mfma_f32_16x16x32_bf16 v[66:69], v[172:175], v[212:215], v[66:69]
	v_mfma_f32_16x16x32_bf16 v[118:121], v[168:171], v[184:187], v[118:121]
	v_mfma_f32_16x16x32_bf16 v[114:117], v[176:179], v[184:187], v[114:117]
	v_mfma_f32_16x16x32_bf16 v[102:105], v[168:171], v[192:195], v[102:105]
	v_mfma_f32_16x16x32_bf16 v[98:101], v[176:179], v[192:195], v[98:101]
	v_mfma_f32_16x16x32_bf16 v[86:89], v[168:171], v[208:211], v[86:89]
	v_mfma_f32_16x16x32_bf16 v[82:85], v[176:179], v[208:211], v[82:85]
	v_mfma_f32_16x16x32_bf16 v[70:73], v[168:171], v[216:219], v[70:73]
	v_mfma_f32_16x16x32_bf16 v[66:69], v[176:179], v[216:219], v[66:69]
	s_barrier
	s_setprio 0
	s_add_i32 s0, s33, s24
	s_mov_b32 m0, s0
	ds_read_b128 v[180:183], v146 offset:16384
	ds_read_b128 v[184:187], v146 offset:17408
	ds_read_b128 v[188:191], v146 offset:18432
	ds_read_b128 v[192:195], v146 offset:19456
	ds_read_b128 v[196:199], v146 offset:20480
	ds_read_b128 v[208:211], v146 offset:21504
	ds_read_b128 v[212:215], v146 offset:22528
	ds_read_b128 v[216:219], v146 offset:23552
	global_load_lds_dwordx4 v134, s[2:3]
	s_add_i32 m0, s0, 0x2000
	s_add_u32 s0, s2, 0x20000
	s_addc_u32 s1, s3, 0
	s_add_i32 s33, s55, s24
	global_load_lds_dwordx4 v130, s[2:3]
	s_mov_b32 m0, s33
	s_nop 0
	global_load_lds_dwordx4 v134, s[0:1]
	s_add_i32 m0, s33, 0x2000
	s_nop 0
	global_load_lds_dwordx4 v130, s[0:1]
	s_mov_b32 m0, s25
	s_nop 0
	global_load_lds_dwordx4 v136, s[4:5]
	s_mov_b32 m0, s26
	s_nop 0
	global_load_lds_dwordx4 v132, s[4:5]
	s_waitcnt vmcnt(8)
	s_waitcnt lgkmcnt(0)
	s_setprio 1
	s_barrier
	v_mfma_f32_16x16x32_bf16 v[62:65], v[148:151], v[180:183], v[62:65]
	v_mfma_f32_16x16x32_bf16 v[58:61], v[156:159], v[180:183], v[58:61]
	v_mfma_f32_16x16x32_bf16 v[46:49], v[148:151], v[188:191], v[46:49]
	v_mfma_f32_16x16x32_bf16 v[42:45], v[156:159], v[188:191], v[42:45]
	v_mfma_f32_16x16x32_bf16 v[30:33], v[148:151], v[196:199], v[30:33]
	v_mfma_f32_16x16x32_bf16 v[26:29], v[156:159], v[196:199], v[26:29]
	v_mfma_f32_16x16x32_bf16 v[14:17], v[148:151], v[212:215], v[14:17]
	v_mfma_f32_16x16x32_bf16 v[10:13], v[156:159], v[212:215], v[10:13]
	v_mfma_f32_16x16x32_bf16 v[62:65], v[152:155], v[184:187], v[62:65]
	v_mfma_f32_16x16x32_bf16 v[58:61], v[160:163], v[184:187], v[58:61]
	v_mfma_f32_16x16x32_bf16 v[46:49], v[152:155], v[192:195], v[46:49]
	v_mfma_f32_16x16x32_bf16 v[42:45], v[160:163], v[192:195], v[42:45]
	v_mfma_f32_16x16x32_bf16 v[30:33], v[152:155], v[208:211], v[30:33]
	v_mfma_f32_16x16x32_bf16 v[26:29], v[160:163], v[208:211], v[26:29]
	v_mfma_f32_16x16x32_bf16 v[14:17], v[152:155], v[216:219], v[14:17]
	v_mfma_f32_16x16x32_bf16 v[10:13], v[160:163], v[216:219], v[10:13]
	v_mfma_f32_16x16x32_bf16 v[54:57], v[164:167], v[180:183], v[54:57]
	v_mfma_f32_16x16x32_bf16 v[50:53], v[172:175], v[180:183], v[50:53]
	v_mfma_f32_16x16x32_bf16 v[38:41], v[164:167], v[188:191], v[38:41]
	v_mfma_f32_16x16x32_bf16 v[34:37], v[172:175], v[188:191], v[34:37]
	v_mfma_f32_16x16x32_bf16 v[22:25], v[164:167], v[196:199], v[22:25]
	v_mfma_f32_16x16x32_bf16 v[18:21], v[172:175], v[196:199], v[18:21]
	v_mfma_f32_16x16x32_bf16 v[6:9], v[164:167], v[212:215], v[6:9]
	v_mfma_f32_16x16x32_bf16 v[2:5], v[172:175], v[212:215], v[2:5]
	v_mfma_f32_16x16x32_bf16 v[54:57], v[168:171], v[184:187], v[54:57]
	v_mfma_f32_16x16x32_bf16 v[50:53], v[176:179], v[184:187], v[50:53]
	v_mfma_f32_16x16x32_bf16 v[38:41], v[168:171], v[192:195], v[38:41]
	v_mfma_f32_16x16x32_bf16 v[34:37], v[176:179], v[192:195], v[34:37]
	v_mfma_f32_16x16x32_bf16 v[22:25], v[168:171], v[208:211], v[22:25]
	v_mfma_f32_16x16x32_bf16 v[18:21], v[176:179], v[208:211], v[18:21]
	v_mfma_f32_16x16x32_bf16 v[6:9], v[168:171], v[216:219], v[6:9]
	v_mfma_f32_16x16x32_bf16 v[2:5], v[176:179], v[216:219], v[2:5]
	s_barrier
	s_setprio 0
	s_add_i32 s33, 0, 0x18000
	s_add_i32 s55, 0, 0x1c000
	ds_read_b128 v[148:151], v143 offset:32768
	ds_read_b128 v[152:155], v143 offset:33792
	ds_read_b128 v[156:159], v143 offset:34816
	ds_read_b128 v[160:163], v143 offset:35840
	ds_read_b128 v[164:167], v143 offset:49152
	ds_read_b128 v[168:171], v143 offset:50176
	ds_read_b128 v[172:175], v143 offset:51200
	ds_read_b128 v[176:179], v143 offset:52224
	s_add_u32 s0, s4, 0x20000
	s_addc_u32 s1, s5, 0
	s_mov_b32 m0, s27
	ds_read_b128 v[180:183], v146 offset:32768
	ds_read_b128 v[184:187], v146 offset:33792
	ds_read_b128 v[188:191], v146 offset:34816
	ds_read_b128 v[192:195], v146 offset:35840
	ds_read_b128 v[196:199], v146 offset:36864
	ds_read_b128 v[208:211], v146 offset:37888
	ds_read_b128 v[212:215], v146 offset:38912
	ds_read_b128 v[216:219], v146 offset:39936
	global_load_lds_dwordx4 v136, s[0:1]
	s_mov_b32 m0, s28
	s_nop 0
	global_load_lds_dwordx4 v132, s[0:1]
	s_waitcnt vmcnt(8)
	s_waitcnt lgkmcnt(0)
	s_setprio 1
	s_barrier
	v_mfma_f32_16x16x32_bf16 v[126:129], v[148:151], v[180:183], v[126:129]
	v_mfma_f32_16x16x32_bf16 v[122:125], v[156:159], v[180:183], v[122:125]
	v_mfma_f32_16x16x32_bf16 v[110:113], v[148:151], v[188:191], v[110:113]
	v_mfma_f32_16x16x32_bf16 v[106:109], v[156:159], v[188:191], v[106:109]
	v_mfma_f32_16x16x32_bf16 v[94:97], v[148:151], v[196:199], v[94:97]
	v_mfma_f32_16x16x32_bf16 v[90:93], v[156:159], v[196:199], v[90:93]
	v_mfma_f32_16x16x32_bf16 v[78:81], v[148:151], v[212:215], v[78:81]
	v_mfma_f32_16x16x32_bf16 v[74:77], v[156:159], v[212:215], v[74:77]
	v_mfma_f32_16x16x32_bf16 v[126:129], v[152:155], v[184:187], v[126:129]
	v_mfma_f32_16x16x32_bf16 v[122:125], v[160:163], v[184:187], v[122:125]
	v_mfma_f32_16x16x32_bf16 v[110:113], v[152:155], v[192:195], v[110:113]
	v_mfma_f32_16x16x32_bf16 v[106:109], v[160:163], v[192:195], v[106:109]
	v_mfma_f32_16x16x32_bf16 v[94:97], v[152:155], v[208:211], v[94:97]
	v_mfma_f32_16x16x32_bf16 v[90:93], v[160:163], v[208:211], v[90:93]
	v_mfma_f32_16x16x32_bf16 v[78:81], v[152:155], v[216:219], v[78:81]
	v_mfma_f32_16x16x32_bf16 v[74:77], v[160:163], v[216:219], v[74:77]
	v_mfma_f32_16x16x32_bf16 v[118:121], v[164:167], v[180:183], v[118:121]
	v_mfma_f32_16x16x32_bf16 v[114:117], v[172:175], v[180:183], v[114:117]
	v_mfma_f32_16x16x32_bf16 v[102:105], v[164:167], v[188:191], v[102:105]
	v_mfma_f32_16x16x32_bf16 v[98:101], v[172:175], v[188:191], v[98:101]
	v_mfma_f32_16x16x32_bf16 v[86:89], v[164:167], v[196:199], v[86:89]
	v_mfma_f32_16x16x32_bf16 v[82:85], v[172:175], v[196:199], v[82:85]
	v_mfma_f32_16x16x32_bf16 v[70:73], v[164:167], v[212:215], v[70:73]
	v_mfma_f32_16x16x32_bf16 v[66:69], v[172:175], v[212:215], v[66:69]
	v_mfma_f32_16x16x32_bf16 v[118:121], v[168:171], v[184:187], v[118:121]
	v_mfma_f32_16x16x32_bf16 v[114:117], v[176:179], v[184:187], v[114:117]
	v_mfma_f32_16x16x32_bf16 v[102:105], v[168:171], v[192:195], v[102:105]
	v_mfma_f32_16x16x32_bf16 v[98:101], v[176:179], v[192:195], v[98:101]
	v_mfma_f32_16x16x32_bf16 v[86:89], v[168:171], v[208:211], v[86:89]
	v_mfma_f32_16x16x32_bf16 v[82:85], v[176:179], v[208:211], v[82:85]
	v_mfma_f32_16x16x32_bf16 v[70:73], v[168:171], v[216:219], v[70:73]
	v_mfma_f32_16x16x32_bf16 v[66:69], v[176:179], v[216:219], v[66:69]
	s_barrier
	s_setprio 0
	s_add_i32 s0, s33, s24
	s_add_u32 s100, s2, 0x80
	s_addc_u32 s101, s3, 0
	s_mov_b32 m0, s0
	ds_read_b128 v[180:183], v146 offset:49152
	ds_read_b128 v[184:187], v146 offset:50176
	ds_read_b128 v[188:191], v146 offset:51200
	ds_read_b128 v[192:195], v146 offset:52224
	ds_read_b128 v[196:199], v146 offset:53248
	ds_read_b128 v[208:211], v146 offset:54272
	ds_read_b128 v[212:215], v146 offset:55296
	ds_read_b128 v[216:219], v146 offset:56320
	global_load_lds_dwordx4 v134, s[100:101]
	s_add_i32 m0, s0, 0x2000
	s_add_u32 s100, s2, 0x80
	s_addc_u32 s101, s3, 0
	s_add_u32 s0, s2, 0x20080
	s_addc_u32 s1, s3, 0
	s_add_i32 s2, s55, s24
	global_load_lds_dwordx4 v130, s[100:101]
	s_mov_b32 m0, s2
	s_nop 0
	global_load_lds_dwordx4 v134, s[0:1]
	s_add_i32 m0, s2, 0x2000
	s_nop 0
	global_load_lds_dwordx4 v130, s[0:1]
	s_add_u32 s100, s4, 0x80
	s_addc_u32 s101, s5, 0
	s_mov_b32 m0, s29
	s_nop 0
	global_load_lds_dwordx4 v136, s[100:101]
	s_add_u32 s100, s4, 0x80
	s_addc_u32 s101, s5, 0
	s_mov_b32 m0, s30
	s_nop 0
	global_load_lds_dwordx4 v132, s[100:101]
	s_add_i32 s59, s59, 2
	s_add_u32 s20, s20, 0x100
	s_addc_u32 s21, s21, 0
	s_add_u32 s49, s49, 0x100
	s_addc_u32 s58, s58, 0
	s_waitcnt vmcnt(8)
	s_waitcnt lgkmcnt(0)
	s_setprio 1
	s_barrier
	v_mfma_f32_16x16x32_bf16 v[62:65], v[148:151], v[180:183], v[62:65]
	v_mfma_f32_16x16x32_bf16 v[58:61], v[156:159], v[180:183], v[58:61]
	v_mfma_f32_16x16x32_bf16 v[46:49], v[148:151], v[188:191], v[46:49]
	v_mfma_f32_16x16x32_bf16 v[42:45], v[156:159], v[188:191], v[42:45]
	v_mfma_f32_16x16x32_bf16 v[30:33], v[148:151], v[196:199], v[30:33]
	v_mfma_f32_16x16x32_bf16 v[26:29], v[156:159], v[196:199], v[26:29]
	v_mfma_f32_16x16x32_bf16 v[14:17], v[148:151], v[212:215], v[14:17]
	v_mfma_f32_16x16x32_bf16 v[10:13], v[156:159], v[212:215], v[10:13]
	v_mfma_f32_16x16x32_bf16 v[62:65], v[152:155], v[184:187], v[62:65]
	v_mfma_f32_16x16x32_bf16 v[58:61], v[160:163], v[184:187], v[58:61]
	v_mfma_f32_16x16x32_bf16 v[46:49], v[152:155], v[192:195], v[46:49]
	v_mfma_f32_16x16x32_bf16 v[42:45], v[160:163], v[192:195], v[42:45]
	v_mfma_f32_16x16x32_bf16 v[30:33], v[152:155], v[208:211], v[30:33]
	v_mfma_f32_16x16x32_bf16 v[26:29], v[160:163], v[208:211], v[26:29]
	v_mfma_f32_16x16x32_bf16 v[14:17], v[152:155], v[216:219], v[14:17]
	v_mfma_f32_16x16x32_bf16 v[10:13], v[160:163], v[216:219], v[10:13]
	v_mfma_f32_16x16x32_bf16 v[54:57], v[164:167], v[180:183], v[54:57]
	v_mfma_f32_16x16x32_bf16 v[50:53], v[172:175], v[180:183], v[50:53]
	v_mfma_f32_16x16x32_bf16 v[38:41], v[164:167], v[188:191], v[38:41]
	v_mfma_f32_16x16x32_bf16 v[34:37], v[172:175], v[188:191], v[34:37]
	v_mfma_f32_16x16x32_bf16 v[22:25], v[164:167], v[196:199], v[22:25]
	v_mfma_f32_16x16x32_bf16 v[18:21], v[172:175], v[196:199], v[18:21]
	v_mfma_f32_16x16x32_bf16 v[6:9], v[164:167], v[212:215], v[6:9]
	v_mfma_f32_16x16x32_bf16 v[2:5], v[172:175], v[212:215], v[2:5]
	v_mfma_f32_16x16x32_bf16 v[54:57], v[168:171], v[184:187], v[54:57]
	v_mfma_f32_16x16x32_bf16 v[50:53], v[176:179], v[184:187], v[50:53]
	v_mfma_f32_16x16x32_bf16 v[38:41], v[168:171], v[192:195], v[38:41]
	v_mfma_f32_16x16x32_bf16 v[34:37], v[176:179], v[192:195], v[34:37]
	v_mfma_f32_16x16x32_bf16 v[22:25], v[168:171], v[208:211], v[22:25]
	v_mfma_f32_16x16x32_bf16 v[18:21], v[176:179], v[208:211], v[18:21]
	v_mfma_f32_16x16x32_bf16 v[6:9], v[168:171], v[216:219], v[6:9]
	v_mfma_f32_16x16x32_bf16 v[2:5], v[176:179], v[216:219], v[2:5]
	s_barrier
	s_setprio 0
	s_cmp_gt_u32 s59, 5
	s_cbranch_scc0 .LBB0_1363
	s_and_b64 vcc, exec, s[14:15]
	s_cbranch_vccz .LBB0_1366
	s_barrier

.LBB0_1428:
	s_add_u32 s0, s26, 0xfff80080
	s_addc_u32 s1, s27, -1
	s_add_i32 s33, 0, 0x10000
	s_cmp_eq_u32 s61, 28
	s_cselect_b32 s5, s17, s1
	s_cselect_b32 s4, s49, s0
	s_cselect_b32 s3, s15, s60
	s_cselect_b32 s2, s58, s59
	s_add_i32 s55, 0, 0x14000
	ds_read_b128 v[126:129], v187
	ds_read_b128 v[134:137], v187 offset:1024
	ds_read_b128 v[138:141], v187 offset:2048
	ds_read_b128 v[142:145], v187 offset:3072
	ds_read_b128 v[146:149], v187 offset:16384
	ds_read_b128 v[150:153], v187 offset:17408
	ds_read_b128 v[154:157], v187 offset:18432
	ds_read_b128 v[158:161], v187 offset:19456
	s_add_i32 m0, s23, 0xc000
	ds_read_b128 v[172:175], v189
	ds_read_b128 v[176:179], v189 offset:1024
	ds_read_b128 v[180:183], v189 offset:2048
	ds_read_b128 v[190:193], v189 offset:3072
	ds_read_b128 v[194:197], v189 offset:4096
	ds_read_b128 v[198:201], v189 offset:5120
	ds_read_b128 v[208:211], v189 offset:6144
	ds_read_b128 v[212:215], v189 offset:7168
	global_load_lds_dwordx4 v168, s[26:27]
	s_add_i32 m0, s23, 0xe000
	s_nop 0
	global_load_lds_dwordx4 v170, s[26:27]
	s_waitcnt vmcnt(8)
	s_waitcnt lgkmcnt(0)
	s_setprio 1
	s_barrier
	v_mfma_f32_16x16x32_bf16 v[130:133], v[126:129], v[172:175], v[130:133]
	v_mfma_f32_16x16x32_bf16 v[118:121], v[138:141], v[172:175], v[118:121]
	v_mfma_f32_16x16x32_bf16 v[110:113], v[126:129], v[180:183], v[110:113]
	v_mfma_f32_16x16x32_bf16 v[102:105], v[138:141], v[180:183], v[102:105]
	v_mfma_f32_16x16x32_bf16 v[94:97], v[126:129], v[194:197], v[94:97]
	v_mfma_f32_16x16x32_bf16 v[86:89], v[138:141], v[194:197], v[86:89]
	v_mfma_f32_16x16x32_bf16 v[78:81], v[126:129], v[208:211], v[78:81]
	v_mfma_f32_16x16x32_bf16 v[70:73], v[138:141], v[208:211], v[70:73]
	v_mfma_f32_16x16x32_bf16 v[130:133], v[134:137], v[176:179], v[130:133]
	v_mfma_f32_16x16x32_bf16 v[118:121], v[142:145], v[176:179], v[118:121]
	v_mfma_f32_16x16x32_bf16 v[110:113], v[134:137], v[190:193], v[110:113]
	v_mfma_f32_16x16x32_bf16 v[102:105], v[142:145], v[190:193], v[102:105]
	v_mfma_f32_16x16x32_bf16 v[94:97], v[134:137], v[198:201], v[94:97]
	v_mfma_f32_16x16x32_bf16 v[86:89], v[142:145], v[198:201], v[86:89]
	v_mfma_f32_16x16x32_bf16 v[78:81], v[134:137], v[212:215], v[78:81]
	v_mfma_f32_16x16x32_bf16 v[70:73], v[142:145], v[212:215], v[70:73]
	v_mfma_f32_16x16x32_bf16 v[122:125], v[146:149], v[172:175], v[122:125]
	v_mfma_f32_16x16x32_bf16 v[114:117], v[154:157], v[172:175], v[114:117]
	v_mfma_f32_16x16x32_bf16 v[106:109], v[146:149], v[180:183], v[106:109]
	v_mfma_f32_16x16x32_bf16 v[98:101], v[154:157], v[180:183], v[98:101]
	v_mfma_f32_16x16x32_bf16 v[90:93], v[146:149], v[194:197], v[90:93]
	v_mfma_f32_16x16x32_bf16 v[82:85], v[154:157], v[194:197], v[82:85]
	v_mfma_f32_16x16x32_bf16 v[74:77], v[146:149], v[208:211], v[74:77]
	v_mfma_f32_16x16x32_bf16 v[66:69], v[154:157], v[208:211], v[66:69]
	v_mfma_f32_16x16x32_bf16 v[122:125], v[150:153], v[176:179], v[122:125]
	v_mfma_f32_16x16x32_bf16 v[114:117], v[158:161], v[176:179], v[114:117]
	v_mfma_f32_16x16x32_bf16 v[106:109], v[150:153], v[190:193], v[106:109]
	v_mfma_f32_16x16x32_bf16 v[98:101], v[158:161], v[190:193], v[98:101]
	v_mfma_f32_16x16x32_bf16 v[90:93], v[150:153], v[198:201], v[90:93]
	v_mfma_f32_16x16x32_bf16 v[82:85], v[158:161], v[198:201], v[82:85]
	v_mfma_f32_16x16x32_bf16 v[74:77], v[150:153], v[212:215], v[74:77]
	v_mfma_f32_16x16x32_bf16 v[66:69], v[158:161], v[212:215], v[66:69]
	s_barrier
	s_setprio 0
	s_add_i32 s0, s33, s34
	s_mov_b32 m0, s0
	ds_read_b128 v[172:175], v189 offset:16384
	ds_read_b128 v[176:179], v189 offset:17408
	ds_read_b128 v[180:183], v189 offset:18432
	ds_read_b128 v[190:193], v189 offset:19456
	ds_read_b128 v[194:197], v189 offset:20480
	ds_read_b128 v[198:201], v189 offset:21504
	ds_read_b128 v[208:211], v189 offset:22528
	ds_read_b128 v[212:215], v189 offset:23552
	global_load_lds_dwordx4 v202, s[2:3]
	s_add_i32 m0, s0, 0x2000
	s_add_u32 s0, s2, 0x80000
	s_addc_u32 s1, s3, 0
	s_add_i32 s33, s55, s34
	global_load_lds_dwordx4 v162, s[2:3]
	s_mov_b32 m0, s33
	s_nop 0
	global_load_lds_dwordx4 v202, s[0:1]
	s_add_i32 m0, s33, 0x2000
	s_nop 0
	global_load_lds_dwordx4 v162, s[0:1]
	s_mov_b32 m0, s23
	s_nop 0
	global_load_lds_dwordx4 v166, s[4:5]
	s_mov_b32 m0, s25
	s_nop 0
	global_load_lds_dwordx4 v164, s[4:5]
	s_waitcnt vmcnt(8)
	s_waitcnt lgkmcnt(0)
	s_setprio 1
	s_barrier
	v_mfma_f32_16x16x32_bf16 v[62:65], v[126:129], v[172:175], v[62:65]
	v_mfma_f32_16x16x32_bf16 v[54:57], v[138:141], v[172:175], v[54:57]
	v_mfma_f32_16x16x32_bf16 v[46:49], v[126:129], v[180:183], v[46:49]
	v_mfma_f32_16x16x32_bf16 v[38:41], v[138:141], v[180:183], v[38:41]
	v_mfma_f32_16x16x32_bf16 v[30:33], v[126:129], v[194:197], v[30:33]
	v_mfma_f32_16x16x32_bf16 v[22:25], v[138:141], v[194:197], v[22:25]
	v_mfma_f32_16x16x32_bf16 v[14:17], v[126:129], v[208:211], v[14:17]
	v_mfma_f32_16x16x32_bf16 v[6:9], v[138:141], v[208:211], v[6:9]
	v_mfma_f32_16x16x32_bf16 v[62:65], v[134:137], v[176:179], v[62:65]
	v_mfma_f32_16x16x32_bf16 v[54:57], v[142:145], v[176:179], v[54:57]
	v_mfma_f32_16x16x32_bf16 v[46:49], v[134:137], v[190:193], v[46:49]
	v_mfma_f32_16x16x32_bf16 v[38:41], v[142:145], v[190:193], v[38:41]
	v_mfma_f32_16x16x32_bf16 v[30:33], v[134:137], v[198:201], v[30:33]
	v_mfma_f32_16x16x32_bf16 v[22:25], v[142:145], v[198:201], v[22:25]
	v_mfma_f32_16x16x32_bf16 v[14:17], v[134:137], v[212:215], v[14:17]
	v_mfma_f32_16x16x32_bf16 v[6:9], v[142:145], v[212:215], v[6:9]
	v_mfma_f32_16x16x32_bf16 v[58:61], v[146:149], v[172:175], v[58:61]
	v_mfma_f32_16x16x32_bf16 v[50:53], v[154:157], v[172:175], v[50:53]
	v_mfma_f32_16x16x32_bf16 v[42:45], v[146:149], v[180:183], v[42:45]
	v_mfma_f32_16x16x32_bf16 v[34:37], v[154:157], v[180:183], v[34:37]
	v_mfma_f32_16x16x32_bf16 v[26:29], v[146:149], v[194:197], v[26:29]
	v_mfma_f32_16x16x32_bf16 v[18:21], v[154:157], v[194:197], v[18:21]
	v_mfma_f32_16x16x32_bf16 v[10:13], v[146:149], v[208:211], v[10:13]
	v_mfma_f32_16x16x32_bf16 v[2:5], v[154:157], v[208:211], v[2:5]
	v_mfma_f32_16x16x32_bf16 v[58:61], v[150:153], v[176:179], v[58:61]
	v_mfma_f32_16x16x32_bf16 v[50:53], v[158:161], v[176:179], v[50:53]
	v_mfma_f32_16x16x32_bf16 v[42:45], v[150:153], v[190:193], v[42:45]
	v_mfma_f32_16x16x32_bf16 v[34:37], v[158:161], v[190:193], v[34:37]
	v_mfma_f32_16x16x32_bf16 v[26:29], v[150:153], v[198:201], v[26:29]
	v_mfma_f32_16x16x32_bf16 v[18:21], v[158:161], v[198:201], v[18:21]
	v_mfma_f32_16x16x32_bf16 v[10:13], v[150:153], v[212:215], v[10:13]
	v_mfma_f32_16x16x32_bf16 v[2:5], v[158:161], v[212:215], v[2:5]
	s_barrier
	s_setprio 0
	s_add_i32 s33, 0, 0x18000
	s_add_i32 s55, 0, 0x1c000
	ds_read_b128 v[126:129], v187 offset:32768
	ds_read_b128 v[134:137], v187 offset:33792
	ds_read_b128 v[138:141], v187 offset:34816
	ds_read_b128 v[142:145], v187 offset:35840
	ds_read_b128 v[146:149], v187 offset:49152
	ds_read_b128 v[150:153], v187 offset:50176
	ds_read_b128 v[154:157], v187 offset:51200
	ds_read_b128 v[158:161], v187 offset:52224
	s_add_u32 s0, s4, 0x80000
	s_addc_u32 s1, s5, 0
	s_mov_b32 m0, s35
	ds_read_b128 v[172:175], v189 offset:32768
	ds_read_b128 v[176:179], v189 offset:33792
	ds_read_b128 v[180:183], v189 offset:34816
	ds_read_b128 v[190:193], v189 offset:35840
	ds_read_b128 v[194:197], v189 offset:36864
	ds_read_b128 v[198:201], v189 offset:37888
	ds_read_b128 v[208:211], v189 offset:38912
	ds_read_b128 v[212:215], v189 offset:39936
	global_load_lds_dwordx4 v166, s[0:1]
	s_mov_b32 m0, s36
	s_nop 0
	global_load_lds_dwordx4 v164, s[0:1]
	s_waitcnt vmcnt(8)
	s_waitcnt lgkmcnt(0)
	s_setprio 1
	s_barrier
	v_mfma_f32_16x16x32_bf16 v[130:133], v[126:129], v[172:175], v[130:133]
	v_mfma_f32_16x16x32_bf16 v[118:121], v[138:141], v[172:175], v[118:121]
	v_mfma_f32_16x16x32_bf16 v[110:113], v[126:129], v[180:183], v[110:113]
	v_mfma_f32_16x16x32_bf16 v[102:105], v[138:141], v[180:183], v[102:105]
	v_mfma_f32_16x16x32_bf16 v[94:97], v[126:129], v[194:197], v[94:97]
	v_mfma_f32_16x16x32_bf16 v[86:89], v[138:141], v[194:197], v[86:89]
	v_mfma_f32_16x16x32_bf16 v[78:81], v[126:129], v[208:211], v[78:81]
	v_mfma_f32_16x16x32_bf16 v[70:73], v[138:141], v[208:211], v[70:73]
	v_mfma_f32_16x16x32_bf16 v[130:133], v[134:137], v[176:179], v[130:133]
	v_mfma_f32_16x16x32_bf16 v[118:121], v[142:145], v[176:179], v[118:121]
	v_mfma_f32_16x16x32_bf16 v[110:113], v[134:137], v[190:193], v[110:113]
	v_mfma_f32_16x16x32_bf16 v[102:105], v[142:145], v[190:193], v[102:105]
	v_mfma_f32_16x16x32_bf16 v[94:97], v[134:137], v[198:201], v[94:97]
	v_mfma_f32_16x16x32_bf16 v[86:89], v[142:145], v[198:201], v[86:89]
	v_mfma_f32_16x16x32_bf16 v[78:81], v[134:137], v[212:215], v[78:81]
	v_mfma_f32_16x16x32_bf16 v[70:73], v[142:145], v[212:215], v[70:73]
	v_mfma_f32_16x16x32_bf16 v[122:125], v[146:149], v[172:175], v[122:125]
	v_mfma_f32_16x16x32_bf16 v[114:117], v[154:157], v[172:175], v[114:117]
	v_mfma_f32_16x16x32_bf16 v[106:109], v[146:149], v[180:183], v[106:109]
	v_mfma_f32_16x16x32_bf16 v[98:101], v[154:157], v[180:183], v[98:101]
	v_mfma_f32_16x16x32_bf16 v[90:93], v[146:149], v[194:197], v[90:93]
	v_mfma_f32_16x16x32_bf16 v[82:85], v[154:157], v[194:197], v[82:85]
	v_mfma_f32_16x16x32_bf16 v[74:77], v[146:149], v[208:211], v[74:77]
	v_mfma_f32_16x16x32_bf16 v[66:69], v[154:157], v[208:211], v[66:69]
	v_mfma_f32_16x16x32_bf16 v[122:125], v[150:153], v[176:179], v[122:125]
	v_mfma_f32_16x16x32_bf16 v[114:117], v[158:161], v[176:179], v[114:117]
	v_mfma_f32_16x16x32_bf16 v[106:109], v[150:153], v[190:193], v[106:109]
	v_mfma_f32_16x16x32_bf16 v[98:101], v[158:161], v[190:193], v[98:101]
	v_mfma_f32_16x16x32_bf16 v[90:93], v[150:153], v[198:201], v[90:93]
	v_mfma_f32_16x16x32_bf16 v[82:85], v[158:161], v[198:201], v[82:85]
	v_mfma_f32_16x16x32_bf16 v[74:77], v[150:153], v[212:215], v[74:77]
	v_mfma_f32_16x16x32_bf16 v[66:69], v[158:161], v[212:215], v[66:69]
	s_barrier
	s_setprio 0
	s_add_i32 s0, s33, s34
	s_add_u32 s100, s2, 0x80
	s_addc_u32 s101, s3, 0
	s_mov_b32 m0, s0
	ds_read_b128 v[172:175], v189 offset:49152
	ds_read_b128 v[176:179], v189 offset:50176
	ds_read_b128 v[180:183], v189 offset:51200
	ds_read_b128 v[190:193], v189 offset:52224
	ds_read_b128 v[194:197], v189 offset:53248
	ds_read_b128 v[198:201], v189 offset:54272
	ds_read_b128 v[208:211], v189 offset:55296
	ds_read_b128 v[212:215], v189 offset:56320
	global_load_lds_dwordx4 v202, s[100:101]
	s_add_i32 m0, s0, 0x2000
	s_add_u32 s100, s2, 0x80
	s_addc_u32 s101, s3, 0
	s_add_u32 s0, s2, 0x80080
	s_addc_u32 s1, s3, 0
	s_add_i32 s2, s55, s34
	global_load_lds_dwordx4 v162, s[100:101]
	s_mov_b32 m0, s2
	s_nop 0
	global_load_lds_dwordx4 v202, s[0:1]
	s_add_i32 m0, s2, 0x2000
	s_nop 0
	global_load_lds_dwordx4 v162, s[0:1]
	s_add_u32 s100, s4, 0x80
	s_addc_u32 s101, s5, 0
	s_mov_b32 m0, s39
	s_nop 0
	global_load_lds_dwordx4 v166, s[100:101]
	s_add_u32 s100, s4, 0x80
	s_addc_u32 s101, s5, 0
	s_mov_b32 m0, s40
	s_nop 0
	global_load_lds_dwordx4 v164, s[100:101]
	s_add_i32 s61, s61, 2
	s_add_u32 s26, s26, 0x100
	s_addc_u32 s27, s27, 0
	s_add_u32 s59, s59, 0x100
	s_addc_u32 s60, s60, 0
	s_waitcnt vmcnt(8)
	s_waitcnt lgkmcnt(0)
	s_setprio 1
	s_barrier
	v_mfma_f32_16x16x32_bf16 v[62:65], v[126:129], v[172:175], v[62:65]
	v_mfma_f32_16x16x32_bf16 v[54:57], v[138:141], v[172:175], v[54:57]
	v_mfma_f32_16x16x32_bf16 v[46:49], v[126:129], v[180:183], v[46:49]
	v_mfma_f32_16x16x32_bf16 v[38:41], v[138:141], v[180:183], v[38:41]
	v_mfma_f32_16x16x32_bf16 v[30:33], v[126:129], v[194:197], v[30:33]
	v_mfma_f32_16x16x32_bf16 v[22:25], v[138:141], v[194:197], v[22:25]
	v_mfma_f32_16x16x32_bf16 v[14:17], v[126:129], v[208:211], v[14:17]
	v_mfma_f32_16x16x32_bf16 v[6:9], v[138:141], v[208:211], v[6:9]
	v_mfma_f32_16x16x32_bf16 v[62:65], v[134:137], v[176:179], v[62:65]
	v_mfma_f32_16x16x32_bf16 v[54:57], v[142:145], v[176:179], v[54:57]
	v_mfma_f32_16x16x32_bf16 v[46:49], v[134:137], v[190:193], v[46:49]
	v_mfma_f32_16x16x32_bf16 v[38:41], v[142:145], v[190:193], v[38:41]
	v_mfma_f32_16x16x32_bf16 v[30:33], v[134:137], v[198:201], v[30:33]
	v_mfma_f32_16x16x32_bf16 v[22:25], v[142:145], v[198:201], v[22:25]
	v_mfma_f32_16x16x32_bf16 v[14:17], v[134:137], v[212:215], v[14:17]
	v_mfma_f32_16x16x32_bf16 v[6:9], v[142:145], v[212:215], v[6:9]
	v_mfma_f32_16x16x32_bf16 v[58:61], v[146:149], v[172:175], v[58:61]
	v_mfma_f32_16x16x32_bf16 v[50:53], v[154:157], v[172:175], v[50:53]
	v_mfma_f32_16x16x32_bf16 v[42:45], v[146:149], v[180:183], v[42:45]
	v_mfma_f32_16x16x32_bf16 v[34:37], v[154:157], v[180:183], v[34:37]
	v_mfma_f32_16x16x32_bf16 v[26:29], v[146:149], v[194:197], v[26:29]
	v_mfma_f32_16x16x32_bf16 v[18:21], v[154:157], v[194:197], v[18:21]
	v_mfma_f32_16x16x32_bf16 v[10:13], v[146:149], v[208:211], v[10:13]
	v_mfma_f32_16x16x32_bf16 v[2:5], v[154:157], v[208:211], v[2:5]
	v_mfma_f32_16x16x32_bf16 v[58:61], v[150:153], v[176:179], v[58:61]
	v_mfma_f32_16x16x32_bf16 v[50:53], v[158:161], v[176:179], v[50:53]
	v_mfma_f32_16x16x32_bf16 v[42:45], v[150:153], v[190:193], v[42:45]
	v_mfma_f32_16x16x32_bf16 v[34:37], v[158:161], v[190:193], v[34:37]
	v_mfma_f32_16x16x32_bf16 v[26:29], v[150:153], v[198:201], v[26:29]
	v_mfma_f32_16x16x32_bf16 v[18:21], v[158:161], v[198:201], v[18:21]
	v_mfma_f32_16x16x32_bf16 v[10:13], v[150:153], v[212:215], v[10:13]
	v_mfma_f32_16x16x32_bf16 v[2:5], v[158:161], v[212:215], v[2:5]
	s_barrier
	s_setprio 0
	s_cmp_gt_u32 s61, 29
	s_cbranch_scc0 .LBB0_1428
	s_and_b64 vcc, exec, s[10:11]
	s_cbranch_vccz .LBB0_1431
	s_barrier

.Lpeel_mid_10:
	s_add_i32 s33, 0, 0x18000
	s_add_i32 s55, 0, 0x1c000
	ds_read_b128 v[146:149], v143 offset:32768
	ds_read_b128 v[150:153], v143 offset:33792
	ds_read_b128 v[154:157], v143 offset:34816
	ds_read_b128 v[158:161], v143 offset:35840
	ds_read_b128 v[162:165], v143 offset:49152
	ds_read_b128 v[166:169], v143 offset:50176
	ds_read_b128 v[170:173], v143 offset:51200
	ds_read_b128 v[174:177], v143 offset:52224
	s_add_u32 s0, s4, 0x80000
	s_addc_u32 s1, s5, 0
	s_mov_b32 m0, s37
	ds_read_b128 v[178:181], v145 offset:32768
	ds_read_b128 v[182:185], v145 offset:33792
	ds_read_b128 v[186:189], v145 offset:34816
	ds_read_b128 v[190:193], v145 offset:35840
	ds_read_b128 v[194:197], v145 offset:36864
	ds_read_b128 v[198:201], v145 offset:37888
	ds_read_b128 v[208:211], v145 offset:38912
	ds_read_b128 v[212:215], v145 offset:39936
	global_load_lds_dwordx4 v134, s[0:1]
	s_mov_b32 m0, s38
	s_nop 0
	global_load_lds_dwordx4 v132, s[0:1]
	s_waitcnt vmcnt(8)
	s_waitcnt lgkmcnt(0)
	s_setprio 1
	s_barrier
	v_mfma_f32_16x16x32_bf16 v[126:129], v[146:149], v[178:181], v[126:129]
	v_mfma_f32_16x16x32_bf16 v[118:121], v[154:157], v[178:181], v[118:121]
	v_mfma_f32_16x16x32_bf16 v[110:113], v[146:149], v[186:189], v[110:113]
	v_mfma_f32_16x16x32_bf16 v[102:105], v[154:157], v[186:189], v[102:105]
	v_mfma_f32_16x16x32_bf16 v[94:97], v[146:149], v[194:197], v[94:97]
	v_mfma_f32_16x16x32_bf16 v[86:89], v[154:157], v[194:197], v[86:89]
	v_mfma_f32_16x16x32_bf16 v[78:81], v[146:149], v[208:211], v[78:81]
	v_mfma_f32_16x16x32_bf16 v[70:73], v[154:157], v[208:211], v[70:73]
	v_mfma_f32_16x16x32_bf16 v[126:129], v[150:153], v[182:185], v[126:129]
	v_mfma_f32_16x16x32_bf16 v[118:121], v[158:161], v[182:185], v[118:121]
	v_mfma_f32_16x16x32_bf16 v[110:113], v[150:153], v[190:193], v[110:113]
	v_mfma_f32_16x16x32_bf16 v[102:105], v[158:161], v[190:193], v[102:105]
	v_mfma_f32_16x16x32_bf16 v[94:97], v[150:153], v[198:201], v[94:97]
	v_mfma_f32_16x16x32_bf16 v[86:89], v[158:161], v[198:201], v[86:89]
	v_mfma_f32_16x16x32_bf16 v[78:81], v[150:153], v[212:215], v[78:81]
	v_mfma_f32_16x16x32_bf16 v[70:73], v[158:161], v[212:215], v[70:73]
	v_mfma_f32_16x16x32_bf16 v[122:125], v[162:165], v[178:181], v[122:125]
	v_mfma_f32_16x16x32_bf16 v[114:117], v[170:173], v[178:181], v[114:117]
	v_mfma_f32_16x16x32_bf16 v[106:109], v[162:165], v[186:189], v[106:109]
	v_mfma_f32_16x16x32_bf16 v[98:101], v[170:173], v[186:189], v[98:101]
	v_mfma_f32_16x16x32_bf16 v[90:93], v[162:165], v[194:197], v[90:93]
	v_mfma_f32_16x16x32_bf16 v[82:85], v[170:173], v[194:197], v[82:85]
	v_mfma_f32_16x16x32_bf16 v[74:77], v[162:165], v[208:211], v[74:77]
	v_mfma_f32_16x16x32_bf16 v[66:69], v[170:173], v[208:211], v[66:69]
	v_mfma_f32_16x16x32_bf16 v[122:125], v[166:169], v[182:185], v[122:125]
	v_mfma_f32_16x16x32_bf16 v[114:117], v[174:177], v[182:185], v[114:117]
	v_mfma_f32_16x16x32_bf16 v[106:109], v[166:169], v[190:193], v[106:109]
	v_mfma_f32_16x16x32_bf16 v[98:101], v[174:177], v[190:193], v[98:101]
	v_mfma_f32_16x16x32_bf16 v[90:93], v[166:169], v[198:201], v[90:93]
	v_mfma_f32_16x16x32_bf16 v[82:85], v[174:177], v[198:201], v[82:85]
	v_mfma_f32_16x16x32_bf16 v[74:77], v[166:169], v[212:215], v[74:77]
	v_mfma_f32_16x16x32_bf16 v[66:69], v[174:177], v[212:215], v[66:69]
	s_barrier
	s_setprio 0
	s_add_i32 s0, s33, s36
	s_add_u32 s100, s2, 0x80
	s_addc_u32 s101, s3, 0
	s_mov_b32 m0, s0
	ds_read_b128 v[178:181], v145 offset:49152
	ds_read_b128 v[182:185], v145 offset:50176
	ds_read_b128 v[186:189], v145 offset:51200
	ds_read_b128 v[190:193], v145 offset:52224
	ds_read_b128 v[194:197], v145 offset:53248
	ds_read_b128 v[198:201], v145 offset:54272
	ds_read_b128 v[208:211], v145 offset:55296
	ds_read_b128 v[212:215], v145 offset:56320
	global_load_lds_dwordx4 v202, s[100:101]
	s_add_i32 m0, s0, 0x2000
	s_add_u32 s100, s2, 0x80
	s_addc_u32 s101, s3, 0
	s_add_u32 s0, s2, 0x80080
	s_addc_u32 s1, s3, 0
	s_add_i32 s2, s55, s36
	global_load_lds_dwordx4 v130, s[100:101]
	s_mov_b32 m0, s2
	s_nop 0
	global_load_lds_dwordx4 v202, s[0:1]
	s_add_i32 m0, s2, 0x2000
	s_nop 0
	global_load_lds_dwordx4 v130, s[0:1]
	s_add_u32 s100, s4, 0x80
	s_addc_u32 s101, s5, 0
	s_mov_b32 m0, s39
	s_nop 0
	global_load_lds_dwordx4 v134, s[100:101]
	s_add_u32 s100, s4, 0x80
	s_addc_u32 s101, s5, 0
	s_mov_b32 m0, s40
	s_nop 0
	global_load_lds_dwordx4 v132, s[100:101]
	s_add_i32 s61, s61, 2
	s_add_u32 s28, s28, 0x100
	s_addc_u32 s29, s29, 0
	s_add_u32 s59, s59, 0x100
	s_addc_u32 s60, s60, 0
	s_waitcnt vmcnt(8)
	s_waitcnt lgkmcnt(0)
	s_setprio 1
	s_barrier
	v_mfma_f32_16x16x32_bf16 v[62:65], v[146:149], v[178:181], v[62:65]
	v_mfma_f32_16x16x32_bf16 v[54:57], v[154:157], v[178:181], v[54:57]
	v_mfma_f32_16x16x32_bf16 v[46:49], v[146:149], v[186:189], v[46:49]
	v_mfma_f32_16x16x32_bf16 v[38:41], v[154:157], v[186:189], v[38:41]
	v_mfma_f32_16x16x32_bf16 v[30:33], v[146:149], v[194:197], v[30:33]
	v_mfma_f32_16x16x32_bf16 v[22:25], v[154:157], v[194:197], v[22:25]
	v_mfma_f32_16x16x32_bf16 v[14:17], v[146:149], v[208:211], v[14:17]
	v_mfma_f32_16x16x32_bf16 v[6:9], v[154:157], v[208:211], v[6:9]
	v_mfma_f32_16x16x32_bf16 v[62:65], v[150:153], v[182:185], v[62:65]
	v_mfma_f32_16x16x32_bf16 v[54:57], v[158:161], v[182:185], v[54:57]
	v_mfma_f32_16x16x32_bf16 v[46:49], v[150:153], v[190:193], v[46:49]
	v_mfma_f32_16x16x32_bf16 v[38:41], v[158:161], v[190:193], v[38:41]
	v_mfma_f32_16x16x32_bf16 v[30:33], v[150:153], v[198:201], v[30:33]
	v_mfma_f32_16x16x32_bf16 v[22:25], v[158:161], v[198:201], v[22:25]
	v_mfma_f32_16x16x32_bf16 v[14:17], v[150:153], v[212:215], v[14:17]
	v_mfma_f32_16x16x32_bf16 v[6:9], v[158:161], v[212:215], v[6:9]
	v_mfma_f32_16x16x32_bf16 v[58:61], v[162:165], v[178:181], v[58:61]
	v_mfma_f32_16x16x32_bf16 v[50:53], v[170:173], v[178:181], v[50:53]
	v_mfma_f32_16x16x32_bf16 v[42:45], v[162:165], v[186:189], v[42:45]
	v_mfma_f32_16x16x32_bf16 v[34:37], v[170:173], v[186:189], v[34:37]
	v_mfma_f32_16x16x32_bf16 v[26:29], v[162:165], v[194:197], v[26:29]
	v_mfma_f32_16x16x32_bf16 v[18:21], v[170:173], v[194:197], v[18:21]
	v_mfma_f32_16x16x32_bf16 v[10:13], v[162:165], v[208:211], v[10:13]
	v_mfma_f32_16x16x32_bf16 v[2:5], v[170:173], v[208:211], v[2:5]
	v_mfma_f32_16x16x32_bf16 v[58:61], v[166:169], v[182:185], v[58:61]
	v_mfma_f32_16x16x32_bf16 v[50:53], v[174:177], v[182:185], v[50:53]
	v_mfma_f32_16x16x32_bf16 v[42:45], v[166:169], v[190:193], v[42:45]
	v_mfma_f32_16x16x32_bf16 v[34:37], v[174:177], v[190:193], v[34:37]
	v_mfma_f32_16x16x32_bf16 v[26:29], v[166:169], v[198:201], v[26:29]
	v_mfma_f32_16x16x32_bf16 v[18:21], v[174:177], v[198:201], v[18:21]
	v_mfma_f32_16x16x32_bf16 v[10:13], v[166:169], v[212:215], v[10:13]
	v_mfma_f32_16x16x32_bf16 v[2:5], v[174:177], v[212:215], v[2:5]
	s_barrier
	s_setprio 0
	s_cmp_gt_u32 s61, 29
	s_cbranch_scc0 .LBB0_1594
	s_mov_b32 s101, 0x80000001
	s_and_b64 vcc, exec, s[14:15]
	s_cbranch_vccz .LBB0_1597
	s_barrier
